# GEMM K-loops: redundant post-barrier lgkmcnt(0) removed and s_setprio 1 moved ahead of the pre-MMA barrier (16 sites)
# speedup vs baseline: 1.0149x; 1.0071x over previous
; #define PG8_STAGE(bufoff, gbase, voff) do { _Pragma("unroll") for (int _i = 0; _i < 2; ++_i) \
;         __builtin_amdgcn_global_load_lds((const unsigned*)((const char*)(gbase) + (voff)[_i]), (PG8_LAS unsigned*)(lds + (bufoff) + ldsw + _i * 8192), 16, 0, 0); } while (0)
; #define PG8_LDA(dst, b, h) do { _Pragma("unroll") for (int m = 0; m < 4; ++m) _Pragma("unroll") for (int k = 0; k < 2; ++k) dst[m][k] = *(const PG8_LAS bf16x8*)(lds + PG8_SA(b, h) + aoff + m * 2048 + k * 1024); } while (0)
; #define PG8_LDB(dst, b, h) do { _Pragma("unroll") for (int n = 0; n < 2; ++n) _Pragma("unroll") for (int k = 0; k < 2; ++k) dst[n][k] = *(const PG8_LAS bf16x8*)(lds + PG8_SB(b, h) + boff + n * 2048 + k * 1024); } while (0)
; #define PG8_MMA(ai, bj, At, Bt) do { __builtin_amdgcn_s_setprio(1); _Pragma("unroll") for (int m = 0; m < 4; ++m) _Pragma("unroll") for (int n = 0; n < 2; ++n) _Pragma("unroll") for (int k = 0; k < 2; ++k) \
;         acc[ai][bj][m][n] = __builtin_amdgcn_mfma_f32_16x16x32_bf16(Bt[n][k], At[m][k], acc[ai][bj][m][n], 0, 0, 0); __builtin_amdgcn_s_setprio(0); } while (0)
; #define PG8_BAR __builtin_amdgcn_s_barrier()
; template <class Epi, class Sched, bool ALIGN_EPI = false, bool SP2 = false>
; __device__ __forceinline__ void gemm_phase(PG8_LAS unsigned char* lds, const Gemm g, const Sched& S, const Epi& E, int tid_in) {
;     ...
;             PG8_LDB(B0, 0, 0); PG8_LDB(B1, 0, 1); PG8_SCHED; PG8_LDA(At, 0, 0); PG8_STAGE(PG8_SA(1, 1), a1 + hstep, voffA);
;             PG8_WAIT_V(8); PG8_WAIT_L(0); PG8_BAR; PG8_MMA(0, 0, At, B0); PG8_MMA(0, 1, At, B1); PG8_BAR; PG8_SCHED;
;             PG8_LDA(At, 0, 1); PG8_STAGE(PG8_SB(0, 0), b2, voffB); PG8_STAGE(PG8_SB(0, 1), b2 + hstep, voffB); PG8_STAGE(PG8_SA(0, 0), a2, voffA);
;             PG8_WAIT_V(8); PG8_WAIT_L(0); PG8_BAR; PG8_MMA(1, 0, At, B0); PG8_MMA(1, 1, At, B1); PG8_BAR; PG8_SCHED;
;             PG8_LDB(B0, 1, 0); PG8_LDB(B1, 1, 1); PG8_SCHED; PG8_LDA(At, 1, 0); PG8_STAGE(PG8_SA(0, 1), a2 + hstep, voffA);
;             PG8_WAIT_V(8); PG8_WAIT_L(0); PG8_BAR; PG8_MMA(0, 0, At, B0); PG8_MMA(0, 1, At, B1); PG8_BAR; PG8_SCHED;
;             PG8_LDA(At, 1, 1); PG8_STAGE(PG8_SB(1, 0), b3, voffB); PG8_STAGE(PG8_SB(1, 1), b3 + hstep, voffB); PG8_STAGE(PG8_SA(1, 0), a3, voffA);
;             PG8_WAIT_V(8); PG8_WAIT_L(0); PG8_BAR; PG8_MMA(1, 0, At, B0); PG8_MMA(1, 1, At, B1); PG8_BAR; PG8_SCHED;
.LBB0_59:
	s_add_u32 s28, s6, 0xfff80080
	s_addc_u32 s29, s7, -1
	s_add_i32 s60, 0, 0x10000
	s_cmp_eq_u32 s59, 28
	s_cselect_b32 s31, s23, s29
	s_cselect_b32 s30, s45, s28
	v_add_u32_e32 v32, s60, v149
	s_cselect_b32 s29, s21, s47
	s_cselect_b32 s28, s57, s58
	s_add_i32 s62, 0, 0x14000
	ds_read_b128 v[142:145], v32
	ds_read_b128 v[152:155], v32 offset:1024
	ds_read_b128 v[156:159], v32 offset:2048
	ds_read_b128 v[160:163], v32 offset:3072
	v_add_u32_e32 v32, s62, v149
	ds_read_b128 v[164:167], v32
	ds_read_b128 v[186:189], v32 offset:1024
	ds_read_b128 v[190:193], v32 offset:2048
	ds_read_b128 v[194:197], v32 offset:3072
	v_lshl_add_u64 v[146:147], s[6:7], 0, v[138:139]
	s_add_i32 m0, s42, 0xc000
	ds_read_b128 v[212:215], v151
	ds_read_b128 v[220:223], v151 offset:1024
	ds_read_b128 v[224:227], v151 offset:2048
	ds_read_b128 v[228:231], v151 offset:3072
	ds_read_b128 v[232:235], v151 offset:4096
	ds_read_b128 v[236:239], v151 offset:5120
	ds_read_b128 v[240:243], v151 offset:6144
	ds_read_b128 v[244:247], v151 offset:7168
	global_load_lds_dwordx4 v[146:147], off
	v_lshl_add_u64 v[146:147], s[6:7], 0, v[140:141]
	s_add_i32 m0, s42, 0xe000
	s_nop 0
	global_load_lds_dwordx4 v[146:147], off
	s_waitcnt vmcnt(8)
	s_waitcnt lgkmcnt(0)
	s_setprio 1
	s_barrier
	v_mfma_f32_16x16x32_bf16 v[126:129], v[142:145], v[212:215], v[126:129]
	v_mfma_f32_16x16x32_bf16 v[122:125], v[156:159], v[212:215], v[122:125]
	v_mfma_f32_16x16x32_bf16 v[110:113], v[142:145], v[224:227], v[110:113]
	v_mfma_f32_16x16x32_bf16 v[106:109], v[156:159], v[224:227], v[106:109]
	v_mfma_f32_16x16x32_bf16 v[94:97], v[142:145], v[232:235], v[94:97]
	v_mfma_f32_16x16x32_bf16 v[90:93], v[156:159], v[232:235], v[90:93]
	v_mfma_f32_16x16x32_bf16 v[78:81], v[142:145], v[240:243], v[78:81]
	v_mfma_f32_16x16x32_bf16 v[74:77], v[156:159], v[240:243], v[74:77]
	v_mfma_f32_16x16x32_bf16 v[126:129], v[152:155], v[220:223], v[126:129]
	v_mfma_f32_16x16x32_bf16 v[122:125], v[160:163], v[220:223], v[122:125]
	v_mfma_f32_16x16x32_bf16 v[110:113], v[152:155], v[228:231], v[110:113]
	v_mfma_f32_16x16x32_bf16 v[106:109], v[160:163], v[228:231], v[106:109]
	v_mfma_f32_16x16x32_bf16 v[94:97], v[152:155], v[236:239], v[94:97]
	v_mfma_f32_16x16x32_bf16 v[90:93], v[160:163], v[236:239], v[90:93]
	v_mfma_f32_16x16x32_bf16 v[78:81], v[152:155], v[244:247], v[78:81]
	v_mfma_f32_16x16x32_bf16 v[74:77], v[160:163], v[244:247], v[74:77]
	s_setprio 0
	s_setprio 1
	v_mfma_f32_16x16x32_bf16 v[118:121], v[164:167], v[212:215], v[118:121]
	v_mfma_f32_16x16x32_bf16 v[114:117], v[190:193], v[212:215], v[114:117]
	v_mfma_f32_16x16x32_bf16 v[102:105], v[164:167], v[224:227], v[102:105]
	v_mfma_f32_16x16x32_bf16 v[98:101], v[190:193], v[224:227], v[98:101]
	v_mfma_f32_16x16x32_bf16 v[86:89], v[164:167], v[232:235], v[86:89]
	v_mfma_f32_16x16x32_bf16 v[82:85], v[190:193], v[232:235], v[82:85]
	v_mfma_f32_16x16x32_bf16 v[70:73], v[164:167], v[240:243], v[70:73]
	v_mfma_f32_16x16x32_bf16 v[66:69], v[190:193], v[240:243], v[66:69]
	v_mfma_f32_16x16x32_bf16 v[118:121], v[186:189], v[220:223], v[118:121]
	v_mfma_f32_16x16x32_bf16 v[114:117], v[194:197], v[220:223], v[114:117]
	v_mfma_f32_16x16x32_bf16 v[102:105], v[186:189], v[228:231], v[102:105]
	v_mfma_f32_16x16x32_bf16 v[98:101], v[194:197], v[228:231], v[98:101]
	v_mfma_f32_16x16x32_bf16 v[86:89], v[186:189], v[236:239], v[86:89]
	v_mfma_f32_16x16x32_bf16 v[82:85], v[194:197], v[236:239], v[82:85]
	v_mfma_f32_16x16x32_bf16 v[70:73], v[186:189], v[244:247], v[70:73]
	v_mfma_f32_16x16x32_bf16 v[66:69], v[194:197], v[244:247], v[66:69]
	s_setprio 0
	s_barrier
	s_add_i32 s60, s60, s39
	v_lshl_add_u64 v[146:147], s[28:29], 0, v[134:135]
	s_mov_b32 m0, s60
	ds_read_b128 v[212:215], v151 offset:16384
	ds_read_b128 v[220:223], v151 offset:17408
	ds_read_b128 v[224:227], v151 offset:18432
	ds_read_b128 v[228:231], v151 offset:19456
	ds_read_b128 v[232:235], v151 offset:20480
	ds_read_b128 v[236:239], v151 offset:21504
	ds_read_b128 v[240:243], v151 offset:22528
	ds_read_b128 v[244:247], v151 offset:23552
	global_load_lds_dwordx4 v[146:147], off
	s_add_i32 m0, s60, 0x2000
	s_add_u32 s60, s28, 0x80000
	v_lshl_add_u64 v[168:169], s[28:29], 0, v[130:131]
	s_addc_u32 s61, s29, 0
	s_add_i32 s62, s62, s39
	global_load_lds_dwordx4 v[168:169], off
	v_lshl_add_u64 v[216:217], s[60:61], 0, v[134:135]
	s_mov_b32 m0, s62
	v_lshl_add_u64 v[248:249], s[30:31], 0, v[132:133]
	global_load_lds_dwordx4 v[216:217], off
	v_lshl_add_u64 v[216:217], s[60:61], 0, v[130:131]
	s_add_i32 m0, s62, 0x2000
	s_nop 0
	global_load_lds_dwordx4 v[216:217], off
	v_lshl_add_u64 v[216:217], s[30:31], 0, v[136:137]
	s_mov_b32 m0, s42
	s_nop 0
	global_load_lds_dwordx4 v[216:217], off
	s_mov_b32 m0, s43
	s_nop 0
	global_load_lds_dwordx4 v[248:249], off
	s_waitcnt vmcnt(8)
	s_waitcnt lgkmcnt(0)
	s_setprio 1
	s_barrier
; #define PG8_STAGE(bufoff, gbase, voff) do { _Pragma("unroll") for (int _i = 0; _i < 2; ++_i) \
;         __builtin_amdgcn_global_load_lds((const unsigned*)((const char*)(gbase) + (voff)[_i]), (PG8_LAS unsigned*)(lds + (bufoff) + ldsw + _i * 8192), 16, 0, 0); } while (0)
; #define PG8_LDA(dst, b, h) do { _Pragma("unroll") for (int m = 0; m < 4; ++m) _Pragma("unroll") for (int k = 0; k < 2; ++k) dst[m][k] = *(const PG8_LAS bf16x8*)(lds + PG8_SA(b, h) + aoff + m * 2048 + k * 1024); } while (0)
; #define PG8_LDB(dst, b, h) do { _Pragma("unroll") for (int n = 0; n < 2; ++n) _Pragma("unroll") for (int k = 0; k < 2; ++k) dst[n][k] = *(const PG8_LAS bf16x8*)(lds + PG8_SB(b, h) + boff + n * 2048 + k * 1024); } while (0)
; #define PG8_MMA(ai, bj, At, Bt) do { __builtin_amdgcn_s_setprio(1); _Pragma("unroll") for (int m = 0; m < 4; ++m) _Pragma("unroll") for (int n = 0; n < 2; ++n) _Pragma("unroll") for (int k = 0; k < 2; ++k) \
;         acc[ai][bj][m][n] = __builtin_amdgcn_mfma_f32_16x16x32_bf16(Bt[n][k], At[m][k], acc[ai][bj][m][n], 0, 0, 0); __builtin_amdgcn_s_setprio(0); } while (0)
; #define PG8_BAR __builtin_amdgcn_s_barrier()
; template <class Epi, class Sched, bool ALIGN_EPI = false, bool SP2 = false>
; __device__ __forceinline__ void gemm_phase(PG8_LAS unsigned char* lds, const Gemm g, const Sched& S, const Epi& E, int tid_in) {
;     ...
;             PG8_LDB(B0, 0, 0); PG8_LDB(B1, 0, 1); PG8_SCHED; PG8_LDA(At, 0, 0); PG8_STAGE(PG8_SA(1, 1), a1 + hstep, voffA);
;             PG8_WAIT_V(8); PG8_WAIT_L(0); PG8_BAR; PG8_MMA(0, 0, At, B0); PG8_MMA(0, 1, At, B1); PG8_BAR; PG8_SCHED;
;             PG8_LDA(At, 0, 1); PG8_STAGE(PG8_SB(0, 0), b2, voffB); PG8_STAGE(PG8_SB(0, 1), b2 + hstep, voffB); PG8_STAGE(PG8_SA(0, 0), a2, voffA);
;             PG8_WAIT_V(8); PG8_WAIT_L(0); PG8_BAR; PG8_MMA(1, 0, At, B0); PG8_MMA(1, 1, At, B1); PG8_BAR; PG8_SCHED;
;             PG8_LDB(B0, 1, 0); PG8_LDB(B1, 1, 1); PG8_SCHED; PG8_LDA(At, 1, 0); PG8_STAGE(PG8_SA(0, 1), a2 + hstep, voffA);
;             PG8_WAIT_V(8); PG8_WAIT_L(0); PG8_BAR; PG8_MMA(0, 0, At, B0); PG8_MMA(0, 1, At, B1); PG8_BAR; PG8_SCHED;
;             PG8_LDA(At, 1, 1); PG8_STAGE(PG8_SB(1, 0), b3, voffB); PG8_STAGE(PG8_SB(1, 1), b3 + hstep, voffB); PG8_STAGE(PG8_SA(1, 0), a3, voffA);
;             PG8_WAIT_V(8); PG8_WAIT_L(0); PG8_BAR; PG8_MMA(1, 0, At, B0); PG8_MMA(1, 1, At, B1); PG8_BAR; PG8_SCHED;
	v_mfma_f32_16x16x32_bf16 v[62:65], v[142:145], v[212:215], v[62:65]
	v_mfma_f32_16x16x32_bf16 v[58:61], v[156:159], v[212:215], v[58:61]
	v_mfma_f32_16x16x32_bf16 v[46:49], v[142:145], v[224:227], v[46:49]
	v_mfma_f32_16x16x32_bf16 v[42:45], v[156:159], v[224:227], v[42:45]
	v_mfma_f32_16x16x32_bf16 v[28:31], v[142:145], v[232:235], v[28:31]
	v_mfma_f32_16x16x32_bf16 v[24:27], v[156:159], v[232:235], v[24:27]
	v_mfma_f32_16x16x32_bf16 v[12:15], v[142:145], v[240:243], v[12:15]
	v_mfma_f32_16x16x32_bf16 v[8:11], v[156:159], v[240:243], v[8:11]
	v_mfma_f32_16x16x32_bf16 v[62:65], v[152:155], v[220:223], v[62:65]
	v_mfma_f32_16x16x32_bf16 v[58:61], v[160:163], v[220:223], v[58:61]
	v_mfma_f32_16x16x32_bf16 v[46:49], v[152:155], v[228:231], v[46:49]
	v_mfma_f32_16x16x32_bf16 v[42:45], v[160:163], v[228:231], v[42:45]
	v_mfma_f32_16x16x32_bf16 v[28:31], v[152:155], v[236:239], v[28:31]
	v_mfma_f32_16x16x32_bf16 v[24:27], v[160:163], v[236:239], v[24:27]
	v_mfma_f32_16x16x32_bf16 v[12:15], v[152:155], v[244:247], v[12:15]
	v_mfma_f32_16x16x32_bf16 v[8:11], v[160:163], v[244:247], v[8:11]
	s_setprio 0
	s_setprio 1
	v_mfma_f32_16x16x32_bf16 v[54:57], v[164:167], v[212:215], v[54:57]
	v_mfma_f32_16x16x32_bf16 v[50:53], v[190:193], v[212:215], v[50:53]
	v_mfma_f32_16x16x32_bf16 v[38:41], v[164:167], v[224:227], v[38:41]
	v_mfma_f32_16x16x32_bf16 v[34:37], v[190:193], v[224:227], v[34:37]
	v_mfma_f32_16x16x32_bf16 v[20:23], v[164:167], v[232:235], v[20:23]
	v_mfma_f32_16x16x32_bf16 v[16:19], v[190:193], v[232:235], v[16:19]
	v_mfma_f32_16x16x32_bf16 v[4:7], v[164:167], v[240:243], v[4:7]
	v_mfma_f32_16x16x32_bf16 v[0:3], v[190:193], v[240:243], v[0:3]
	v_mfma_f32_16x16x32_bf16 v[54:57], v[186:189], v[220:223], v[54:57]
	v_mfma_f32_16x16x32_bf16 v[50:53], v[194:197], v[220:223], v[50:53]
	v_mfma_f32_16x16x32_bf16 v[38:41], v[186:189], v[228:231], v[38:41]
	v_mfma_f32_16x16x32_bf16 v[34:37], v[194:197], v[228:231], v[34:37]
	v_mfma_f32_16x16x32_bf16 v[20:23], v[186:189], v[236:239], v[20:23]
	v_mfma_f32_16x16x32_bf16 v[16:19], v[194:197], v[236:239], v[16:19]
	v_mfma_f32_16x16x32_bf16 v[4:7], v[186:189], v[244:247], v[4:7]
	v_mfma_f32_16x16x32_bf16 v[0:3], v[194:197], v[244:247], v[0:3]
	s_setprio 0
	s_barrier
	s_add_i32 s60, 0, 0x18000
	v_add_u32_e32 v32, s60, v149
	s_add_i32 s61, 0, 0x1c000
	ds_read_b128 v[142:145], v32
	ds_read_b128 v[152:155], v32 offset:1024
	ds_read_b128 v[156:159], v32 offset:2048
	ds_read_b128 v[160:163], v32 offset:3072
	v_add_u32_e32 v32, s61, v149
	ds_read_b128 v[164:167], v32
	ds_read_b128 v[186:189], v32 offset:1024
	ds_read_b128 v[190:193], v32 offset:2048
	ds_read_b128 v[194:197], v32 offset:3072
	s_add_u32 s30, s30, 0x80000
	s_addc_u32 s31, s31, 0
	s_mov_b32 m0, s48
	v_lshl_add_u64 v[250:251], s[30:31], 0, v[136:137]
	ds_read_b128 v[212:215], v151 offset:32768
	ds_read_b128 v[220:223], v151 offset:33792
	ds_read_b128 v[224:227], v151 offset:34816
	ds_read_b128 v[228:231], v151 offset:35840
	ds_read_b128 v[232:235], v151 offset:36864
	ds_read_b128 v[236:239], v151 offset:37888
	ds_read_b128 v[240:243], v151 offset:38912
	ds_read_b128 v[244:247], v151 offset:39936
	global_load_lds_dwordx4 v[250:251], off
	v_lshl_add_u64 v[250:251], s[30:31], 0, v[132:133]
	s_mov_b32 m0, s49
	s_nop 0
	global_load_lds_dwordx4 v[250:251], off
	s_waitcnt vmcnt(8)
	s_waitcnt lgkmcnt(0)
	s_setprio 1
	s_barrier
	v_mfma_f32_16x16x32_bf16 v[126:129], v[142:145], v[212:215], v[126:129]
	v_mfma_f32_16x16x32_bf16 v[122:125], v[156:159], v[212:215], v[122:125]
	v_mfma_f32_16x16x32_bf16 v[110:113], v[142:145], v[224:227], v[110:113]
	v_mfma_f32_16x16x32_bf16 v[106:109], v[156:159], v[224:227], v[106:109]
	v_mfma_f32_16x16x32_bf16 v[94:97], v[142:145], v[232:235], v[94:97]
	v_mfma_f32_16x16x32_bf16 v[90:93], v[156:159], v[232:235], v[90:93]
	v_mfma_f32_16x16x32_bf16 v[78:81], v[142:145], v[240:243], v[78:81]
	v_mfma_f32_16x16x32_bf16 v[74:77], v[156:159], v[240:243], v[74:77]
	v_mfma_f32_16x16x32_bf16 v[126:129], v[152:155], v[220:223], v[126:129]
	v_mfma_f32_16x16x32_bf16 v[122:125], v[160:163], v[220:223], v[122:125]
	v_mfma_f32_16x16x32_bf16 v[110:113], v[152:155], v[228:231], v[110:113]
	v_mfma_f32_16x16x32_bf16 v[106:109], v[160:163], v[228:231], v[106:109]
	v_mfma_f32_16x16x32_bf16 v[94:97], v[152:155], v[236:239], v[94:97]
	v_mfma_f32_16x16x32_bf16 v[90:93], v[160:163], v[236:239], v[90:93]
	v_mfma_f32_16x16x32_bf16 v[78:81], v[152:155], v[244:247], v[78:81]
	v_mfma_f32_16x16x32_bf16 v[74:77], v[160:163], v[244:247], v[74:77]
	s_setprio 0
	s_setprio 1
	v_mfma_f32_16x16x32_bf16 v[118:121], v[164:167], v[212:215], v[118:121]
	v_mfma_f32_16x16x32_bf16 v[114:117], v[190:193], v[212:215], v[114:117]
	v_mfma_f32_16x16x32_bf16 v[102:105], v[164:167], v[224:227], v[102:105]
	v_mfma_f32_16x16x32_bf16 v[98:101], v[190:193], v[224:227], v[98:101]
	v_mfma_f32_16x16x32_bf16 v[86:89], v[164:167], v[232:235], v[86:89]
	v_mfma_f32_16x16x32_bf16 v[82:85], v[190:193], v[232:235], v[82:85]
	v_mfma_f32_16x16x32_bf16 v[70:73], v[164:167], v[240:243], v[70:73]
	v_mfma_f32_16x16x32_bf16 v[66:69], v[190:193], v[240:243], v[66:69]
	v_mfma_f32_16x16x32_bf16 v[118:121], v[186:189], v[220:223], v[118:121]
	v_mfma_f32_16x16x32_bf16 v[114:117], v[194:197], v[220:223], v[114:117]
	v_mfma_f32_16x16x32_bf16 v[102:105], v[186:189], v[228:231], v[102:105]
	v_mfma_f32_16x16x32_bf16 v[98:101], v[194:197], v[228:231], v[98:101]
	v_mfma_f32_16x16x32_bf16 v[86:89], v[186:189], v[236:239], v[86:89]
	v_mfma_f32_16x16x32_bf16 v[82:85], v[194:197], v[236:239], v[82:85]
	v_mfma_f32_16x16x32_bf16 v[70:73], v[186:189], v[244:247], v[70:73]
	v_mfma_f32_16x16x32_bf16 v[66:69], v[194:197], v[244:247], v[66:69]
	s_setprio 0
	s_barrier
; #define PG8_STAGE(bufoff, gbase, voff) do { _Pragma("unroll") for (int _i = 0; _i < 2; ++_i) \
;         __builtin_amdgcn_global_load_lds((const unsigned*)((const char*)(gbase) + (voff)[_i]), (PG8_LAS unsigned*)(lds + (bufoff) + ldsw + _i * 8192), 16, 0, 0); } while (0)
; #define PG8_LDA(dst, b, h) do { _Pragma("unroll") for (int m = 0; m < 4; ++m) _Pragma("unroll") for (int k = 0; k < 2; ++k) dst[m][k] = *(const PG8_LAS bf16x8*)(lds + PG8_SA(b, h) + aoff + m * 2048 + k * 1024); } while (0)
; #define PG8_LDB(dst, b, h) do { _Pragma("unroll") for (int n = 0; n < 2; ++n) _Pragma("unroll") for (int k = 0; k < 2; ++k) dst[n][k] = *(const PG8_LAS bf16x8*)(lds + PG8_SB(b, h) + boff + n * 2048 + k * 1024); } while (0)
; #define PG8_MMA(ai, bj, At, Bt) do { __builtin_amdgcn_s_setprio(1); _Pragma("unroll") for (int m = 0; m < 4; ++m) _Pragma("unroll") for (int n = 0; n < 2; ++n) _Pragma("unroll") for (int k = 0; k < 2; ++k) \
;         acc[ai][bj][m][n] = __builtin_amdgcn_mfma_f32_16x16x32_bf16(Bt[n][k], At[m][k], acc[ai][bj][m][n], 0, 0, 0); __builtin_amdgcn_s_setprio(0); } while (0)
; #define PG8_BAR __builtin_amdgcn_s_barrier()
; template <class Epi, class Sched, bool ALIGN_EPI = false, bool SP2 = false>
; __device__ __forceinline__ void gemm_phase(PG8_LAS unsigned char* lds, const Gemm g, const Sched& S, const Epi& E, int tid_in) {
;     ...
;             PG8_LDB(B0, 0, 0); PG8_LDB(B1, 0, 1); PG8_SCHED; PG8_LDA(At, 0, 0); PG8_STAGE(PG8_SA(1, 1), a1 + hstep, voffA);
;             PG8_WAIT_V(8); PG8_WAIT_L(0); PG8_BAR; PG8_MMA(0, 0, At, B0); PG8_MMA(0, 1, At, B1); PG8_BAR; PG8_SCHED;
;             PG8_LDA(At, 0, 1); PG8_STAGE(PG8_SB(0, 0), b2, voffB); PG8_STAGE(PG8_SB(0, 1), b2 + hstep, voffB); PG8_STAGE(PG8_SA(0, 0), a2, voffA);
;             PG8_WAIT_V(8); PG8_WAIT_L(0); PG8_BAR; PG8_MMA(1, 0, At, B0); PG8_MMA(1, 1, At, B1); PG8_BAR; PG8_SCHED;
;             PG8_LDB(B0, 1, 0); PG8_LDB(B1, 1, 1); PG8_SCHED; PG8_LDA(At, 1, 0); PG8_STAGE(PG8_SA(0, 1), a2 + hstep, voffA);
;             PG8_WAIT_V(8); PG8_WAIT_L(0); PG8_BAR; PG8_MMA(0, 0, At, B0); PG8_MMA(0, 1, At, B1); PG8_BAR; PG8_SCHED;
;             PG8_LDA(At, 1, 1); PG8_STAGE(PG8_SB(1, 0), b3, voffB); PG8_STAGE(PG8_SB(1, 1), b3 + hstep, voffB); PG8_STAGE(PG8_SA(1, 0), a3, voffA);
;             PG8_WAIT_V(8); PG8_WAIT_L(0); PG8_BAR; PG8_MMA(1, 0, At, B0); PG8_MMA(1, 1, At, B1); PG8_BAR; PG8_SCHED;
	s_add_i32 s30, s60, s39
	v_lshl_add_u64 v[146:147], v[146:147], 0, s[74:75]
	s_mov_b32 m0, s30
	ds_read_b128 v[212:215], v151 offset:49152
	ds_read_b128 v[220:223], v151 offset:50176
	ds_read_b128 v[224:227], v151 offset:51200
	ds_read_b128 v[228:231], v151 offset:52224
	ds_read_b128 v[232:235], v151 offset:53248
	ds_read_b128 v[236:239], v151 offset:54272
	ds_read_b128 v[240:243], v151 offset:55296
	ds_read_b128 v[244:247], v151 offset:56320
	global_load_lds_dwordx4 v[146:147], off
	s_add_i32 m0, s30, 0x2000
	s_add_u32 s28, s28, 0x80080
	v_lshl_add_u64 v[146:147], v[168:169], 0, s[74:75]
	s_addc_u32 s29, s29, 0
	s_add_i32 s30, s61, s39
	global_load_lds_dwordx4 v[146:147], off
	v_lshl_add_u64 v[146:147], s[28:29], 0, v[134:135]
	s_mov_b32 m0, s30
	s_nop 0
	global_load_lds_dwordx4 v[146:147], off
	v_lshl_add_u64 v[146:147], s[28:29], 0, v[130:131]
	s_add_i32 m0, s30, 0x2000
	s_nop 0
	global_load_lds_dwordx4 v[146:147], off
	v_lshl_add_u64 v[146:147], v[216:217], 0, s[74:75]
	s_mov_b32 m0, s50
	s_nop 0
	global_load_lds_dwordx4 v[146:147], off
	v_lshl_add_u64 v[146:147], v[248:249], 0, s[74:75]
	s_mov_b32 m0, s51
	s_nop 0
	global_load_lds_dwordx4 v[146:147], off
	s_waitcnt vmcnt(8)
	s_waitcnt lgkmcnt(0)
	s_setprio 1
	s_barrier
	v_mfma_f32_16x16x32_bf16 v[62:65], v[142:145], v[212:215], v[62:65]
	v_mfma_f32_16x16x32_bf16 v[58:61], v[156:159], v[212:215], v[58:61]
	v_mfma_f32_16x16x32_bf16 v[46:49], v[142:145], v[224:227], v[46:49]
	v_mfma_f32_16x16x32_bf16 v[42:45], v[156:159], v[224:227], v[42:45]
	v_mfma_f32_16x16x32_bf16 v[28:31], v[142:145], v[232:235], v[28:31]
	v_mfma_f32_16x16x32_bf16 v[24:27], v[156:159], v[232:235], v[24:27]
	v_mfma_f32_16x16x32_bf16 v[12:15], v[142:145], v[240:243], v[12:15]
	v_mfma_f32_16x16x32_bf16 v[8:11], v[156:159], v[240:243], v[8:11]
	v_mfma_f32_16x16x32_bf16 v[62:65], v[152:155], v[220:223], v[62:65]
	v_mfma_f32_16x16x32_bf16 v[58:61], v[160:163], v[220:223], v[58:61]
	v_mfma_f32_16x16x32_bf16 v[46:49], v[152:155], v[228:231], v[46:49]
	v_mfma_f32_16x16x32_bf16 v[42:45], v[160:163], v[228:231], v[42:45]
	v_mfma_f32_16x16x32_bf16 v[28:31], v[152:155], v[236:239], v[28:31]
	v_mfma_f32_16x16x32_bf16 v[24:27], v[160:163], v[236:239], v[24:27]
	v_mfma_f32_16x16x32_bf16 v[12:15], v[152:155], v[244:247], v[12:15]
	v_mfma_f32_16x16x32_bf16 v[8:11], v[160:163], v[244:247], v[8:11]
	s_setprio 0
	s_setprio 1
	v_mfma_f32_16x16x32_bf16 v[54:57], v[164:167], v[212:215], v[54:57]
	v_mfma_f32_16x16x32_bf16 v[50:53], v[190:193], v[212:215], v[50:53]
	v_mfma_f32_16x16x32_bf16 v[38:41], v[164:167], v[224:227], v[38:41]
	v_mfma_f32_16x16x32_bf16 v[34:37], v[190:193], v[224:227], v[34:37]
	v_mfma_f32_16x16x32_bf16 v[20:23], v[164:167], v[232:235], v[20:23]
	v_mfma_f32_16x16x32_bf16 v[16:19], v[190:193], v[232:235], v[16:19]
	v_mfma_f32_16x16x32_bf16 v[4:7], v[164:167], v[240:243], v[4:7]
	v_mfma_f32_16x16x32_bf16 v[0:3], v[190:193], v[240:243], v[0:3]
	v_mfma_f32_16x16x32_bf16 v[54:57], v[186:189], v[220:223], v[54:57]
	v_mfma_f32_16x16x32_bf16 v[50:53], v[194:197], v[220:223], v[50:53]
	v_mfma_f32_16x16x32_bf16 v[38:41], v[186:189], v[228:231], v[38:41]
	v_mfma_f32_16x16x32_bf16 v[34:37], v[194:197], v[228:231], v[34:37]
	v_mfma_f32_16x16x32_bf16 v[20:23], v[186:189], v[236:239], v[20:23]
	v_mfma_f32_16x16x32_bf16 v[16:19], v[194:197], v[236:239], v[16:19]
	v_mfma_f32_16x16x32_bf16 v[4:7], v[186:189], v[244:247], v[4:7]
	v_mfma_f32_16x16x32_bf16 v[0:3], v[194:197], v[244:247], v[0:3]
	s_setprio 0
	s_barrier
	s_add_i32 s59, s59, 2
	s_add_u32 s6, s6, 0x100
	s_addc_u32 s7, s7, 0
	s_add_u32 s58, s58, 0x100
	s_addc_u32 s47, s47, 0
	s_cmp_gt_u32 s59, 29
	s_cbranch_scc0 .LBB0_59
	s_and_b64 vcc, exec, s[16:17]
	s_cbranch_vccz .LBB0_62
	s_barrier

; #define PG8_STAGE(bufoff, gbase, voff) do { _Pragma("unroll") for (int _i = 0; _i < 2; ++_i) \
;         __builtin_amdgcn_global_load_lds((const unsigned*)((const char*)(gbase) + (voff)[_i]), (PG8_LAS unsigned*)(lds + (bufoff) + ldsw + _i * 8192), 16, 0, 0); } while (0)
; #define PG8_LDA(dst, b, h) do { _Pragma("unroll") for (int m = 0; m < 4; ++m) _Pragma("unroll") for (int k = 0; k < 2; ++k) dst[m][k] = *(const PG8_LAS bf16x8*)(lds + PG8_SA(b, h) + aoff + m * 2048 + k * 1024); } while (0)
; #define PG8_LDB(dst, b, h) do { _Pragma("unroll") for (int n = 0; n < 2; ++n) _Pragma("unroll") for (int k = 0; k < 2; ++k) dst[n][k] = *(const PG8_LAS bf16x8*)(lds + PG8_SB(b, h) + boff + n * 2048 + k * 1024); } while (0)
; #define PG8_MMA(ai, bj, At, Bt) do { __builtin_amdgcn_s_setprio(1); _Pragma("unroll") for (int m = 0; m < 4; ++m) _Pragma("unroll") for (int n = 0; n < 2; ++n) _Pragma("unroll") for (int k = 0; k < 2; ++k) \
;         acc[ai][bj][m][n] = __builtin_amdgcn_mfma_f32_16x16x32_bf16(Bt[n][k], At[m][k], acc[ai][bj][m][n], 0, 0, 0); __builtin_amdgcn_s_setprio(0); } while (0)
; #define PG8_BAR __builtin_amdgcn_s_barrier()
; template <class Epi, class Sched, bool ALIGN_EPI = false, bool SP2 = false>
; __device__ __forceinline__ void gemm_phase(PG8_LAS unsigned char* lds, const Gemm g, const Sched& S, const Epi& E, int tid_in) {
;     ...
;             PG8_LDB(B0, 0, 0); PG8_LDB(B1, 0, 1); PG8_SCHED; PG8_LDA(At, 0, 0); PG8_STAGE(PG8_SA(1, 1), a1 + hstep, voffA);
;             PG8_WAIT_V(8); PG8_WAIT_L(0); PG8_BAR; PG8_MMA(0, 0, At, B0); PG8_MMA(0, 1, At, B1); PG8_BAR; PG8_SCHED;
;             PG8_LDA(At, 0, 1); PG8_STAGE(PG8_SB(0, 0), b2, voffB); PG8_STAGE(PG8_SB(0, 1), b2 + hstep, voffB); PG8_STAGE(PG8_SA(0, 0), a2, voffA);
;             PG8_WAIT_V(8); PG8_WAIT_L(0); PG8_BAR; PG8_MMA(1, 0, At, B0); PG8_MMA(1, 1, At, B1); PG8_BAR; PG8_SCHED;
;             PG8_LDB(B0, 1, 0); PG8_LDB(B1, 1, 1); PG8_SCHED; PG8_LDA(At, 1, 0); PG8_STAGE(PG8_SA(0, 1), a2 + hstep, voffA);
;             PG8_WAIT_V(8); PG8_WAIT_L(0); PG8_BAR; PG8_MMA(0, 0, At, B0); PG8_MMA(0, 1, At, B1); PG8_BAR; PG8_SCHED;
;             PG8_LDA(At, 1, 1); PG8_STAGE(PG8_SB(1, 0), b3, voffB); PG8_STAGE(PG8_SB(1, 1), b3 + hstep, voffB); PG8_STAGE(PG8_SA(1, 0), a3, voffA);
;             PG8_WAIT_V(8); PG8_WAIT_L(0); PG8_BAR; PG8_MMA(1, 0, At, B0); PG8_MMA(1, 1, At, B1); PG8_BAR; PG8_SCHED;
.LBB0_349:
	s_add_u32 s26, s24, 0x100
	s_addc_u32 s27, s25, 0
	s_add_i32 s60, 0, 0x10000
	s_cmp_eq_u32 s59, 28
	s_cselect_b32 s31, s19, s27
	s_cselect_b32 s30, s45, s26
	s_cselect_b32 s29, s17, s58
	s_cselect_b32 s28, s57, s47
	s_add_i32 s61, 0, 0x14000
	v_add_u32_e32 v152, s60, v141
	v_add_u32_e32 v168, s61, v141
	ds_read_b128 v[136:139], v152
	ds_read_b128 v[144:147], v152 offset:1024
	ds_read_b128 v[148:151], v152 offset:2048
	ds_read_b128 v[152:155], v152 offset:3072
	ds_read_b128 v[156:159], v168
	ds_read_b128 v[160:163], v168 offset:1024
	ds_read_b128 v[164:167], v168 offset:2048
	ds_read_b128 v[186:189], v168 offset:3072
	v_lshl_add_u64 v[168:169], s[24:25], 0, v[132:133]
	s_add_i32 m0, s39, 0xc000
	ds_read_b128 v[190:193], v143
	ds_read_b128 v[194:197], v143 offset:1024
	ds_read_b128 v[212:215], v143 offset:2048
	ds_read_b128 v[220:223], v143 offset:3072
	ds_read_b128 v[224:227], v143 offset:4096
	ds_read_b128 v[228:231], v143 offset:5120
	ds_read_b128 v[232:235], v143 offset:6144
	ds_read_b128 v[236:239], v143 offset:7168
	global_load_lds_dwordx4 v[168:169], off
	v_lshl_add_u64 v[168:169], s[24:25], 0, v[134:135]
	s_add_i32 m0, s39, 0xe000
	s_nop 0
	global_load_lds_dwordx4 v[168:169], off
	s_waitcnt vmcnt(8)
	s_waitcnt lgkmcnt(0)
	s_setprio 1
	s_barrier
	v_mfma_f32_16x16x32_bf16 v[126:129], v[136:139], v[190:193], v[126:129]
	v_mfma_f32_16x16x32_bf16 v[122:125], v[148:151], v[190:193], v[122:125]
	v_mfma_f32_16x16x32_bf16 v[114:117], v[136:139], v[212:215], v[114:117]
	v_mfma_f32_16x16x32_bf16 v[110:113], v[148:151], v[212:215], v[110:113]
	v_mfma_f32_16x16x32_bf16 v[98:101], v[136:139], v[224:227], v[98:101]
	v_mfma_f32_16x16x32_bf16 v[94:97], v[148:151], v[224:227], v[94:97]
	v_mfma_f32_16x16x32_bf16 v[82:85], v[136:139], v[232:235], v[82:85]
	v_mfma_f32_16x16x32_bf16 v[78:81], v[148:151], v[232:235], v[78:81]
	v_mfma_f32_16x16x32_bf16 v[126:129], v[144:147], v[194:197], v[126:129]
	v_mfma_f32_16x16x32_bf16 v[122:125], v[152:155], v[194:197], v[122:125]
	v_mfma_f32_16x16x32_bf16 v[114:117], v[144:147], v[220:223], v[114:117]
	v_mfma_f32_16x16x32_bf16 v[110:113], v[152:155], v[220:223], v[110:113]
	v_mfma_f32_16x16x32_bf16 v[98:101], v[144:147], v[228:231], v[98:101]
	v_mfma_f32_16x16x32_bf16 v[94:97], v[152:155], v[228:231], v[94:97]
	v_mfma_f32_16x16x32_bf16 v[82:85], v[144:147], v[236:239], v[82:85]
	v_mfma_f32_16x16x32_bf16 v[78:81], v[152:155], v[236:239], v[78:81]
	s_setprio 0
	s_setprio 1
	v_mfma_f32_16x16x32_bf16 v[118:121], v[156:159], v[190:193], v[118:121]
	v_mfma_f32_16x16x32_bf16 v[106:109], v[164:167], v[190:193], v[106:109]
	v_mfma_f32_16x16x32_bf16 v[102:105], v[156:159], v[212:215], v[102:105]
	v_mfma_f32_16x16x32_bf16 v[90:93], v[164:167], v[212:215], v[90:93]
	v_mfma_f32_16x16x32_bf16 v[86:89], v[156:159], v[224:227], v[86:89]
	v_mfma_f32_16x16x32_bf16 v[74:77], v[164:167], v[224:227], v[74:77]
	v_mfma_f32_16x16x32_bf16 v[70:73], v[156:159], v[232:235], v[70:73]
	v_mfma_f32_16x16x32_bf16 v[66:69], v[164:167], v[232:235], v[66:69]
	v_mfma_f32_16x16x32_bf16 v[118:121], v[160:163], v[194:197], v[118:121]
	v_mfma_f32_16x16x32_bf16 v[106:109], v[186:189], v[194:197], v[106:109]
	v_mfma_f32_16x16x32_bf16 v[102:105], v[160:163], v[220:223], v[102:105]
	v_mfma_f32_16x16x32_bf16 v[90:93], v[186:189], v[220:223], v[90:93]
	v_mfma_f32_16x16x32_bf16 v[86:89], v[160:163], v[228:231], v[86:89]
	v_mfma_f32_16x16x32_bf16 v[74:77], v[186:189], v[228:231], v[74:77]
	v_mfma_f32_16x16x32_bf16 v[70:73], v[160:163], v[236:239], v[70:73]
	v_mfma_f32_16x16x32_bf16 v[66:69], v[186:189], v[236:239], v[66:69]
	s_setprio 0
	s_barrier
	s_add_i32 s24, s60, s4
	v_lshl_add_u64 v[168:169], s[28:29], 0, v[32:33]
	s_mov_b32 m0, s24
	ds_read_b128 v[190:193], v143 offset:16384
	ds_read_b128 v[194:197], v143 offset:17408
	ds_read_b128 v[212:215], v143 offset:18432
	ds_read_b128 v[220:223], v143 offset:19456
	ds_read_b128 v[224:227], v143 offset:20480
	ds_read_b128 v[228:231], v143 offset:21504
	ds_read_b128 v[232:235], v143 offset:22528
	ds_read_b128 v[236:239], v143 offset:23552
	global_load_lds_dwordx4 v[168:169], off
	s_add_i32 m0, s24, 0x2000
	s_add_u32 s24, s28, 0x80000
	v_lshl_add_u64 v[216:217], s[28:29], 0, v[130:131]
	s_addc_u32 s25, s29, 0
	s_add_i32 s60, s61, s4
	global_load_lds_dwordx4 v[216:217], off
	v_lshl_add_u64 v[240:241], s[24:25], 0, v[32:33]
	s_mov_b32 m0, s60
	v_lshl_add_u64 v[242:243], s[30:31], 0, v[130:131]
	global_load_lds_dwordx4 v[240:241], off
	v_lshl_add_u64 v[240:241], s[24:25], 0, v[130:131]
	s_add_i32 m0, s60, 0x2000
	s_nop 0
	global_load_lds_dwordx4 v[240:241], off
	v_lshl_add_u64 v[240:241], s[30:31], 0, v[32:33]
	s_mov_b32 m0, s39
	s_nop 0
	global_load_lds_dwordx4 v[240:241], off
	s_mov_b32 m0, s42
	s_nop 0
	global_load_lds_dwordx4 v[242:243], off
	s_waitcnt vmcnt(8)
	s_waitcnt lgkmcnt(0)
	s_setprio 1
	s_barrier
; #define PG8_STAGE(bufoff, gbase, voff) do { _Pragma("unroll") for (int _i = 0; _i < 2; ++_i) \
;         __builtin_amdgcn_global_load_lds((const unsigned*)((const char*)(gbase) + (voff)[_i]), (PG8_LAS unsigned*)(lds + (bufoff) + ldsw + _i * 8192), 16, 0, 0); } while (0)
; #define PG8_LDA(dst, b, h) do { _Pragma("unroll") for (int m = 0; m < 4; ++m) _Pragma("unroll") for (int k = 0; k < 2; ++k) dst[m][k] = *(const PG8_LAS bf16x8*)(lds + PG8_SA(b, h) + aoff + m * 2048 + k * 1024); } while (0)
; #define PG8_LDB(dst, b, h) do { _Pragma("unroll") for (int n = 0; n < 2; ++n) _Pragma("unroll") for (int k = 0; k < 2; ++k) dst[n][k] = *(const PG8_LAS bf16x8*)(lds + PG8_SB(b, h) + boff + n * 2048 + k * 1024); } while (0)
; #define PG8_MMA(ai, bj, At, Bt) do { __builtin_amdgcn_s_setprio(1); _Pragma("unroll") for (int m = 0; m < 4; ++m) _Pragma("unroll") for (int n = 0; n < 2; ++n) _Pragma("unroll") for (int k = 0; k < 2; ++k) \
;         acc[ai][bj][m][n] = __builtin_amdgcn_mfma_f32_16x16x32_bf16(Bt[n][k], At[m][k], acc[ai][bj][m][n], 0, 0, 0); __builtin_amdgcn_s_setprio(0); } while (0)
; #define PG8_BAR __builtin_amdgcn_s_barrier()
; template <class Epi, class Sched, bool ALIGN_EPI = false, bool SP2 = false>
; __device__ __forceinline__ void gemm_phase(PG8_LAS unsigned char* lds, const Gemm g, const Sched& S, const Epi& E, int tid_in) {
;     ...
;             PG8_LDB(B0, 0, 0); PG8_LDB(B1, 0, 1); PG8_SCHED; PG8_LDA(At, 0, 0); PG8_STAGE(PG8_SA(1, 1), a1 + hstep, voffA);
;             PG8_WAIT_V(8); PG8_WAIT_L(0); PG8_BAR; PG8_MMA(0, 0, At, B0); PG8_MMA(0, 1, At, B1); PG8_BAR; PG8_SCHED;
;             PG8_LDA(At, 0, 1); PG8_STAGE(PG8_SB(0, 0), b2, voffB); PG8_STAGE(PG8_SB(0, 1), b2 + hstep, voffB); PG8_STAGE(PG8_SA(0, 0), a2, voffA);
;             PG8_WAIT_V(8); PG8_WAIT_L(0); PG8_BAR; PG8_MMA(1, 0, At, B0); PG8_MMA(1, 1, At, B1); PG8_BAR; PG8_SCHED;
;             PG8_LDB(B0, 1, 0); PG8_LDB(B1, 1, 1); PG8_SCHED; PG8_LDA(At, 1, 0); PG8_STAGE(PG8_SA(0, 1), a2 + hstep, voffA);
;             PG8_WAIT_V(8); PG8_WAIT_L(0); PG8_BAR; PG8_MMA(0, 0, At, B0); PG8_MMA(0, 1, At, B1); PG8_BAR; PG8_SCHED;
;             PG8_LDA(At, 1, 1); PG8_STAGE(PG8_SB(1, 0), b3, voffB); PG8_STAGE(PG8_SB(1, 1), b3 + hstep, voffB); PG8_STAGE(PG8_SA(1, 0), a3, voffA);
;             PG8_WAIT_V(8); PG8_WAIT_L(0); PG8_BAR; PG8_MMA(1, 0, At, B0); PG8_MMA(1, 1, At, B1); PG8_BAR; PG8_SCHED;
	v_mfma_f32_16x16x32_bf16 v[62:65], v[136:139], v[190:193], v[62:65]
	v_mfma_f32_16x16x32_bf16 v[58:61], v[148:151], v[190:193], v[58:61]
	v_mfma_f32_16x16x32_bf16 v[50:53], v[136:139], v[212:215], v[50:53]
	v_mfma_f32_16x16x32_bf16 v[46:49], v[148:151], v[212:215], v[46:49]
	v_mfma_f32_16x16x32_bf16 v[34:37], v[136:139], v[224:227], v[34:37]
	v_mfma_f32_16x16x32_bf16 v[28:31], v[148:151], v[224:227], v[28:31]
	v_mfma_f32_16x16x32_bf16 v[16:19], v[136:139], v[232:235], v[16:19]
	v_mfma_f32_16x16x32_bf16 v[12:15], v[148:151], v[232:235], v[12:15]
	v_mfma_f32_16x16x32_bf16 v[62:65], v[144:147], v[194:197], v[62:65]
	v_mfma_f32_16x16x32_bf16 v[58:61], v[152:155], v[194:197], v[58:61]
	v_mfma_f32_16x16x32_bf16 v[50:53], v[144:147], v[220:223], v[50:53]
	v_mfma_f32_16x16x32_bf16 v[46:49], v[152:155], v[220:223], v[46:49]
	v_mfma_f32_16x16x32_bf16 v[34:37], v[144:147], v[228:231], v[34:37]
	v_mfma_f32_16x16x32_bf16 v[28:31], v[152:155], v[228:231], v[28:31]
	v_mfma_f32_16x16x32_bf16 v[16:19], v[144:147], v[236:239], v[16:19]
	v_mfma_f32_16x16x32_bf16 v[12:15], v[152:155], v[236:239], v[12:15]
	s_setprio 0
	s_setprio 1
	v_mfma_f32_16x16x32_bf16 v[54:57], v[156:159], v[190:193], v[54:57]
	v_mfma_f32_16x16x32_bf16 v[42:45], v[164:167], v[190:193], v[42:45]
	v_mfma_f32_16x16x32_bf16 v[38:41], v[156:159], v[212:215], v[38:41]
	v_mfma_f32_16x16x32_bf16 v[24:27], v[164:167], v[212:215], v[24:27]
	v_mfma_f32_16x16x32_bf16 v[20:23], v[156:159], v[224:227], v[20:23]
	v_mfma_f32_16x16x32_bf16 v[8:11], v[164:167], v[224:227], v[8:11]
	v_mfma_f32_16x16x32_bf16 v[4:7], v[156:159], v[232:235], v[4:7]
	v_mfma_f32_16x16x32_bf16 v[0:3], v[164:167], v[232:235], v[0:3]
	v_mfma_f32_16x16x32_bf16 v[54:57], v[160:163], v[194:197], v[54:57]
	v_mfma_f32_16x16x32_bf16 v[42:45], v[186:189], v[194:197], v[42:45]
	v_mfma_f32_16x16x32_bf16 v[38:41], v[160:163], v[220:223], v[38:41]
	v_mfma_f32_16x16x32_bf16 v[24:27], v[186:189], v[220:223], v[24:27]
	v_mfma_f32_16x16x32_bf16 v[20:23], v[160:163], v[228:231], v[20:23]
	v_mfma_f32_16x16x32_bf16 v[8:11], v[186:189], v[228:231], v[8:11]
	v_mfma_f32_16x16x32_bf16 v[4:7], v[160:163], v[236:239], v[4:7]
	v_mfma_f32_16x16x32_bf16 v[0:3], v[186:189], v[236:239], v[0:3]
	s_setprio 0
	s_barrier
	s_add_i32 s60, 0, 0x18000
	s_add_i32 s61, 0, 0x1c000
	v_add_u32_e32 v152, s60, v141
	v_add_u32_e32 v170, s61, v141
	ds_read_b128 v[136:139], v152
	ds_read_b128 v[144:147], v152 offset:1024
	ds_read_b128 v[148:151], v152 offset:2048
	ds_read_b128 v[152:155], v152 offset:3072
	ds_read_b128 v[156:159], v170
	ds_read_b128 v[160:163], v170 offset:1024
	ds_read_b128 v[164:167], v170 offset:2048
	ds_read_b128 v[186:189], v170 offset:3072
	s_add_u32 s24, s30, 0x80000
	s_addc_u32 s25, s31, 0
	s_mov_b32 m0, s43
	v_lshl_add_u64 v[244:245], s[24:25], 0, v[32:33]
	ds_read_b128 v[190:193], v143 offset:32768
	ds_read_b128 v[194:197], v143 offset:33792
	ds_read_b128 v[212:215], v143 offset:34816
	ds_read_b128 v[220:223], v143 offset:35840
	ds_read_b128 v[224:227], v143 offset:36864
	ds_read_b128 v[228:231], v143 offset:37888
	ds_read_b128 v[232:235], v143 offset:38912
	ds_read_b128 v[236:239], v143 offset:39936
	global_load_lds_dwordx4 v[244:245], off
	v_lshl_add_u64 v[244:245], s[24:25], 0, v[130:131]
	s_mov_b32 m0, s48
	s_nop 0
	global_load_lds_dwordx4 v[244:245], off
	s_waitcnt vmcnt(8)
	s_waitcnt lgkmcnt(0)
	s_setprio 1
	s_barrier
	v_mfma_f32_16x16x32_bf16 v[126:129], v[136:139], v[190:193], v[126:129]
	v_mfma_f32_16x16x32_bf16 v[122:125], v[148:151], v[190:193], v[122:125]
	v_mfma_f32_16x16x32_bf16 v[114:117], v[136:139], v[212:215], v[114:117]
	v_mfma_f32_16x16x32_bf16 v[110:113], v[148:151], v[212:215], v[110:113]
	v_mfma_f32_16x16x32_bf16 v[98:101], v[136:139], v[224:227], v[98:101]
	v_mfma_f32_16x16x32_bf16 v[94:97], v[148:151], v[224:227], v[94:97]
	v_mfma_f32_16x16x32_bf16 v[82:85], v[136:139], v[232:235], v[82:85]
	v_mfma_f32_16x16x32_bf16 v[78:81], v[148:151], v[232:235], v[78:81]
	v_mfma_f32_16x16x32_bf16 v[126:129], v[144:147], v[194:197], v[126:129]
	v_mfma_f32_16x16x32_bf16 v[122:125], v[152:155], v[194:197], v[122:125]
	v_mfma_f32_16x16x32_bf16 v[114:117], v[144:147], v[220:223], v[114:117]
	v_mfma_f32_16x16x32_bf16 v[110:113], v[152:155], v[220:223], v[110:113]
	v_mfma_f32_16x16x32_bf16 v[98:101], v[144:147], v[228:231], v[98:101]
	v_mfma_f32_16x16x32_bf16 v[94:97], v[152:155], v[228:231], v[94:97]
	v_mfma_f32_16x16x32_bf16 v[82:85], v[144:147], v[236:239], v[82:85]
	v_mfma_f32_16x16x32_bf16 v[78:81], v[152:155], v[236:239], v[78:81]
	s_setprio 0
	s_setprio 1
	v_mfma_f32_16x16x32_bf16 v[118:121], v[156:159], v[190:193], v[118:121]
	v_mfma_f32_16x16x32_bf16 v[106:109], v[164:167], v[190:193], v[106:109]
	v_mfma_f32_16x16x32_bf16 v[102:105], v[156:159], v[212:215], v[102:105]
	v_mfma_f32_16x16x32_bf16 v[90:93], v[164:167], v[212:215], v[90:93]
	v_mfma_f32_16x16x32_bf16 v[86:89], v[156:159], v[224:227], v[86:89]
	v_mfma_f32_16x16x32_bf16 v[74:77], v[164:167], v[224:227], v[74:77]
	v_mfma_f32_16x16x32_bf16 v[70:73], v[156:159], v[232:235], v[70:73]
	v_mfma_f32_16x16x32_bf16 v[66:69], v[164:167], v[232:235], v[66:69]
	v_mfma_f32_16x16x32_bf16 v[118:121], v[160:163], v[194:197], v[118:121]
	v_mfma_f32_16x16x32_bf16 v[106:109], v[186:189], v[194:197], v[106:109]
	v_mfma_f32_16x16x32_bf16 v[102:105], v[160:163], v[220:223], v[102:105]
	v_mfma_f32_16x16x32_bf16 v[90:93], v[186:189], v[220:223], v[90:93]
	v_mfma_f32_16x16x32_bf16 v[86:89], v[160:163], v[228:231], v[86:89]
	v_mfma_f32_16x16x32_bf16 v[74:77], v[186:189], v[228:231], v[74:77]
	v_mfma_f32_16x16x32_bf16 v[70:73], v[160:163], v[236:239], v[70:73]
	v_mfma_f32_16x16x32_bf16 v[66:69], v[186:189], v[236:239], v[66:69]
	s_setprio 0
	s_barrier
; #define PG8_STAGE(bufoff, gbase, voff) do { _Pragma("unroll") for (int _i = 0; _i < 2; ++_i) \
;         __builtin_amdgcn_global_load_lds((const unsigned*)((const char*)(gbase) + (voff)[_i]), (PG8_LAS unsigned*)(lds + (bufoff) + ldsw + _i * 8192), 16, 0, 0); } while (0)
; #define PG8_LDA(dst, b, h) do { _Pragma("unroll") for (int m = 0; m < 4; ++m) _Pragma("unroll") for (int k = 0; k < 2; ++k) dst[m][k] = *(const PG8_LAS bf16x8*)(lds + PG8_SA(b, h) + aoff + m * 2048 + k * 1024); } while (0)
; #define PG8_LDB(dst, b, h) do { _Pragma("unroll") for (int n = 0; n < 2; ++n) _Pragma("unroll") for (int k = 0; k < 2; ++k) dst[n][k] = *(const PG8_LAS bf16x8*)(lds + PG8_SB(b, h) + boff + n * 2048 + k * 1024); } while (0)
; #define PG8_MMA(ai, bj, At, Bt) do { __builtin_amdgcn_s_setprio(1); _Pragma("unroll") for (int m = 0; m < 4; ++m) _Pragma("unroll") for (int n = 0; n < 2; ++n) _Pragma("unroll") for (int k = 0; k < 2; ++k) \
;         acc[ai][bj][m][n] = __builtin_amdgcn_mfma_f32_16x16x32_bf16(Bt[n][k], At[m][k], acc[ai][bj][m][n], 0, 0, 0); __builtin_amdgcn_s_setprio(0); } while (0)
; #define PG8_BAR __builtin_amdgcn_s_barrier()
; template <class Epi, class Sched, bool ALIGN_EPI = false, bool SP2 = false>
; __device__ __forceinline__ void gemm_phase(PG8_LAS unsigned char* lds, const Gemm g, const Sched& S, const Epi& E, int tid_in) {
;     ...
;             PG8_LDB(B0, 0, 0); PG8_LDB(B1, 0, 1); PG8_SCHED; PG8_LDA(At, 0, 0); PG8_STAGE(PG8_SA(1, 1), a1 + hstep, voffA);
;             PG8_WAIT_V(8); PG8_WAIT_L(0); PG8_BAR; PG8_MMA(0, 0, At, B0); PG8_MMA(0, 1, At, B1); PG8_BAR; PG8_SCHED;
;             PG8_LDA(At, 0, 1); PG8_STAGE(PG8_SB(0, 0), b2, voffB); PG8_STAGE(PG8_SB(0, 1), b2 + hstep, voffB); PG8_STAGE(PG8_SA(0, 0), a2, voffA);
;             PG8_WAIT_V(8); PG8_WAIT_L(0); PG8_BAR; PG8_MMA(1, 0, At, B0); PG8_MMA(1, 1, At, B1); PG8_BAR; PG8_SCHED;
;             PG8_LDB(B0, 1, 0); PG8_LDB(B1, 1, 1); PG8_SCHED; PG8_LDA(At, 1, 0); PG8_STAGE(PG8_SA(0, 1), a2 + hstep, voffA);
;             PG8_WAIT_V(8); PG8_WAIT_L(0); PG8_BAR; PG8_MMA(0, 0, At, B0); PG8_MMA(0, 1, At, B1); PG8_BAR; PG8_SCHED;
;             PG8_LDA(At, 1, 1); PG8_STAGE(PG8_SB(1, 0), b3, voffB); PG8_STAGE(PG8_SB(1, 1), b3 + hstep, voffB); PG8_STAGE(PG8_SA(1, 0), a3, voffA);
;             PG8_WAIT_V(8); PG8_WAIT_L(0); PG8_BAR; PG8_MMA(1, 0, At, B0); PG8_MMA(1, 1, At, B1); PG8_BAR; PG8_SCHED;
	s_add_i32 s24, s60, s4
	v_lshl_add_u64 v[168:169], v[168:169], 0, s[74:75]
	s_mov_b32 m0, s24
	ds_read_b128 v[190:193], v143 offset:49152
	ds_read_b128 v[194:197], v143 offset:50176
	ds_read_b128 v[212:215], v143 offset:51200
	ds_read_b128 v[220:223], v143 offset:52224
	ds_read_b128 v[224:227], v143 offset:53248
	ds_read_b128 v[228:231], v143 offset:54272
	ds_read_b128 v[232:235], v143 offset:55296
	ds_read_b128 v[236:239], v143 offset:56320
	global_load_lds_dwordx4 v[168:169], off
	s_add_i32 m0, s24, 0x2000
	s_add_u32 s24, s28, 0x80080
	v_lshl_add_u64 v[168:169], v[216:217], 0, s[74:75]
	s_addc_u32 s25, s29, 0
	s_add_i32 s28, s61, s4
	global_load_lds_dwordx4 v[168:169], off
	v_lshl_add_u64 v[168:169], s[24:25], 0, v[32:33]
	s_mov_b32 m0, s28
	s_nop 0
	global_load_lds_dwordx4 v[168:169], off
	v_lshl_add_u64 v[168:169], s[24:25], 0, v[130:131]
	s_add_i32 m0, s28, 0x2000
	s_nop 0
	global_load_lds_dwordx4 v[168:169], off
	v_lshl_add_u64 v[168:169], v[240:241], 0, s[74:75]
	s_mov_b32 m0, s49
	s_nop 0
	global_load_lds_dwordx4 v[168:169], off
	v_lshl_add_u64 v[168:169], v[242:243], 0, s[74:75]
	s_mov_b32 m0, s51
	s_nop 0
	global_load_lds_dwordx4 v[168:169], off
	s_waitcnt vmcnt(8)
	s_waitcnt lgkmcnt(0)
	s_setprio 1
	s_barrier
	v_mfma_f32_16x16x32_bf16 v[62:65], v[136:139], v[190:193], v[62:65]
	v_mfma_f32_16x16x32_bf16 v[58:61], v[148:151], v[190:193], v[58:61]
	v_mfma_f32_16x16x32_bf16 v[50:53], v[136:139], v[212:215], v[50:53]
	v_mfma_f32_16x16x32_bf16 v[46:49], v[148:151], v[212:215], v[46:49]
	v_mfma_f32_16x16x32_bf16 v[34:37], v[136:139], v[224:227], v[34:37]
	v_mfma_f32_16x16x32_bf16 v[28:31], v[148:151], v[224:227], v[28:31]
	v_mfma_f32_16x16x32_bf16 v[16:19], v[136:139], v[232:235], v[16:19]
	v_mfma_f32_16x16x32_bf16 v[12:15], v[148:151], v[232:235], v[12:15]
	v_mfma_f32_16x16x32_bf16 v[62:65], v[144:147], v[194:197], v[62:65]
	v_mfma_f32_16x16x32_bf16 v[58:61], v[152:155], v[194:197], v[58:61]
	v_mfma_f32_16x16x32_bf16 v[50:53], v[144:147], v[220:223], v[50:53]
	v_mfma_f32_16x16x32_bf16 v[46:49], v[152:155], v[220:223], v[46:49]
	v_mfma_f32_16x16x32_bf16 v[34:37], v[144:147], v[228:231], v[34:37]
	v_mfma_f32_16x16x32_bf16 v[28:31], v[152:155], v[228:231], v[28:31]
	v_mfma_f32_16x16x32_bf16 v[16:19], v[144:147], v[236:239], v[16:19]
	v_mfma_f32_16x16x32_bf16 v[12:15], v[152:155], v[236:239], v[12:15]
	s_setprio 0
	s_setprio 1
	v_mfma_f32_16x16x32_bf16 v[54:57], v[156:159], v[190:193], v[54:57]
	v_mfma_f32_16x16x32_bf16 v[42:45], v[164:167], v[190:193], v[42:45]
	v_mfma_f32_16x16x32_bf16 v[38:41], v[156:159], v[212:215], v[38:41]
	v_mfma_f32_16x16x32_bf16 v[24:27], v[164:167], v[212:215], v[24:27]
	v_mfma_f32_16x16x32_bf16 v[20:23], v[156:159], v[224:227], v[20:23]
	v_mfma_f32_16x16x32_bf16 v[8:11], v[164:167], v[224:227], v[8:11]
	v_mfma_f32_16x16x32_bf16 v[4:7], v[156:159], v[232:235], v[4:7]
	v_mfma_f32_16x16x32_bf16 v[0:3], v[164:167], v[232:235], v[0:3]
	v_mfma_f32_16x16x32_bf16 v[54:57], v[160:163], v[194:197], v[54:57]
	v_mfma_f32_16x16x32_bf16 v[42:45], v[186:189], v[194:197], v[42:45]
	v_mfma_f32_16x16x32_bf16 v[38:41], v[160:163], v[220:223], v[38:41]
	v_mfma_f32_16x16x32_bf16 v[24:27], v[186:189], v[220:223], v[24:27]
	v_mfma_f32_16x16x32_bf16 v[20:23], v[160:163], v[228:231], v[20:23]
	v_mfma_f32_16x16x32_bf16 v[8:11], v[186:189], v[228:231], v[8:11]
	v_mfma_f32_16x16x32_bf16 v[4:7], v[160:163], v[236:239], v[4:7]
	v_mfma_f32_16x16x32_bf16 v[0:3], v[186:189], v[236:239], v[0:3]
	s_setprio 0
	s_barrier
	s_add_i32 s59, s59, 2
	s_add_u32 s47, s47, 0x100
	s_addc_u32 s58, s58, 0
	s_cmp_gt_u32 s59, 29
	s_mov_b64 s[24:25], s[26:27]
	s_cbranch_scc0 .LBB0_349
	s_and_b64 vcc, exec, s[14:15]
	s_cbranch_vccz .LBB0_352
	s_barrier

; #define PG8_STAGE(bufoff, gbase, voff) do { _Pragma("unroll") for (int _i = 0; _i < 2; ++_i) \
;         __builtin_amdgcn_global_load_lds((const unsigned*)((const char*)(gbase) + (voff)[_i]), (PG8_LAS unsigned*)(lds + (bufoff) + ldsw + _i * 8192), 16, 0, 0); } while (0)
; #define PG8_LDA(dst, b, h) do { _Pragma("unroll") for (int m = 0; m < 4; ++m) _Pragma("unroll") for (int k = 0; k < 2; ++k) dst[m][k] = *(const PG8_LAS bf16x8*)(lds + PG8_SA(b, h) + aoff + m * 2048 + k * 1024); } while (0)
; #define PG8_LDB(dst, b, h) do { _Pragma("unroll") for (int n = 0; n < 2; ++n) _Pragma("unroll") for (int k = 0; k < 2; ++k) dst[n][k] = *(const PG8_LAS bf16x8*)(lds + PG8_SB(b, h) + boff + n * 2048 + k * 1024); } while (0)
; #define PG8_MMA(ai, bj, At, Bt) do { __builtin_amdgcn_s_setprio(1); _Pragma("unroll") for (int m = 0; m < 4; ++m) _Pragma("unroll") for (int n = 0; n < 2; ++n) _Pragma("unroll") for (int k = 0; k < 2; ++k) \
;         acc[ai][bj][m][n] = __builtin_amdgcn_mfma_f32_16x16x32_bf16(Bt[n][k], At[m][k], acc[ai][bj][m][n], 0, 0, 0); __builtin_amdgcn_s_setprio(0); } while (0)
; #define PG8_BAR __builtin_amdgcn_s_barrier()
; template <class Epi, class Sched, bool ALIGN_EPI = false, bool SP2 = false>
; __device__ __forceinline__ void gemm_phase(PG8_LAS unsigned char* lds, const Gemm g, const Sched& S, const Epi& E, int tid_in) {
;     ...
;             PG8_LDB(B0, 0, 0); PG8_LDB(B1, 0, 1); PG8_SCHED; PG8_LDA(At, 0, 0); PG8_STAGE(PG8_SA(1, 1), a1 + hstep, voffA);
;             PG8_WAIT_V(8); PG8_WAIT_L(0); PG8_BAR; PG8_MMA(0, 0, At, B0); PG8_MMA(0, 1, At, B1); PG8_BAR; PG8_SCHED;
;             PG8_LDA(At, 0, 1); PG8_STAGE(PG8_SB(0, 0), b2, voffB); PG8_STAGE(PG8_SB(0, 1), b2 + hstep, voffB); PG8_STAGE(PG8_SA(0, 0), a2, voffA);
;             PG8_WAIT_V(8); PG8_WAIT_L(0); PG8_BAR; PG8_MMA(1, 0, At, B0); PG8_MMA(1, 1, At, B1); PG8_BAR; PG8_SCHED;
;             PG8_LDB(B0, 1, 0); PG8_LDB(B1, 1, 1); PG8_SCHED; PG8_LDA(At, 1, 0); PG8_STAGE(PG8_SA(0, 1), a2 + hstep, voffA);
;             PG8_WAIT_V(8); PG8_WAIT_L(0); PG8_BAR; PG8_MMA(0, 0, At, B0); PG8_MMA(0, 1, At, B1); PG8_BAR; PG8_SCHED;
;             PG8_LDA(At, 1, 1); PG8_STAGE(PG8_SB(1, 0), b3, voffB); PG8_STAGE(PG8_SB(1, 1), b3 + hstep, voffB); PG8_STAGE(PG8_SA(1, 0), a3, voffA);
;             PG8_WAIT_V(8); PG8_WAIT_L(0); PG8_BAR; PG8_MMA(1, 0, At, B0); PG8_MMA(1, 1, At, B1); PG8_BAR; PG8_SCHED;
.LBB0_479:
	s_add_u32 s16, s56, 0xfff80080
	s_addc_u32 s17, s57, -1
	s_add_i32 s18, 0, 0x10000
	s_cmp_eq_u32 s82, 28
	s_cselect_b32 s63, s71, s17
	s_cselect_b32 s62, vcc_lo, s16
	s_cselect_b32 s61, s59, s77
	s_cselect_b32 s60, vcc_hi, s47
	s_add_i32 s19, 0, 0x14000
	v_add_u32_e32 v78, s18, v172
	v_add_u32_e32 v102, s19, v172
	ds_read_b128 v[66:69], v78
	ds_read_b128 v[70:73], v78 offset:1024
	ds_read_b128 v[74:77], v78 offset:2048
	ds_read_b128 v[78:81], v78 offset:3072
	ds_read_b128 v[86:89], v102
	ds_read_b128 v[90:93], v102 offset:1024
	ds_read_b128 v[94:97], v102 offset:2048
	ds_read_b128 v[102:105], v102 offset:3072
	v_lshl_add_u64 v[196:197], s[56:57], 0, v[192:193]
	s_add_i32 m0, s68, 0xc000
	ds_read_b128 v[162:165], v217
	ds_read_b128 v[166:169], v217 offset:1024
	ds_read_b128 v[220:223], v217 offset:2048
	ds_read_b128 v[224:227], v217 offset:3072
	ds_read_b128 v[228:231], v217 offset:4096
	ds_read_b128 v[232:235], v217 offset:5120
	ds_read_b128 v[236:239], v217 offset:6144
	ds_read_b128 v[240:243], v217 offset:7168
	global_load_lds_dwordx4 v[196:197], off
	v_lshl_add_u64 v[196:197], s[56:57], 0, v[194:195]
	s_add_i32 m0, s68, 0xe000
	s_nop 0
	global_load_lds_dwordx4 v[196:197], off
	s_waitcnt vmcnt(8)
	s_waitcnt lgkmcnt(0)
	s_setprio 1
	s_barrier
	v_mfma_f32_16x16x32_bf16 v[150:153], v[66:69], v[162:165], v[150:153]
	v_mfma_f32_16x16x32_bf16 v[146:149], v[74:77], v[162:165], v[146:149]
	v_mfma_f32_16x16x32_bf16 v[138:141], v[66:69], v[220:223], v[138:141]
	v_mfma_f32_16x16x32_bf16 v[130:133], v[74:77], v[220:223], v[130:133]
	v_mfma_f32_16x16x32_bf16 v[122:125], v[66:69], v[228:231], v[122:125]
	v_mfma_f32_16x16x32_bf16 v[110:113], v[74:77], v[228:231], v[110:113]
	v_mfma_f32_16x16x32_bf16 v[114:117], v[66:69], v[236:239], v[114:117]
	v_mfma_f32_16x16x32_bf16 v[98:101], v[74:77], v[236:239], v[98:101]
	v_mfma_f32_16x16x32_bf16 v[150:153], v[70:73], v[166:169], v[150:153]
	v_mfma_f32_16x16x32_bf16 v[146:149], v[78:81], v[166:169], v[146:149]
	v_mfma_f32_16x16x32_bf16 v[138:141], v[70:73], v[224:227], v[138:141]
	v_mfma_f32_16x16x32_bf16 v[130:133], v[78:81], v[224:227], v[130:133]
	v_mfma_f32_16x16x32_bf16 v[122:125], v[70:73], v[232:235], v[122:125]
	v_mfma_f32_16x16x32_bf16 v[110:113], v[78:81], v[232:235], v[110:113]
	v_mfma_f32_16x16x32_bf16 v[114:117], v[70:73], v[240:243], v[114:117]
	v_mfma_f32_16x16x32_bf16 v[98:101], v[78:81], v[240:243], v[98:101]
	s_setprio 0
	s_setprio 1
	v_mfma_f32_16x16x32_bf16 v[158:161], v[86:89], v[162:165], v[158:161]
	v_mfma_f32_16x16x32_bf16 v[154:157], v[94:97], v[162:165], v[154:157]
	v_mfma_f32_16x16x32_bf16 v[142:145], v[86:89], v[220:223], v[142:145]
	v_mfma_f32_16x16x32_bf16 v[134:137], v[94:97], v[220:223], v[134:137]
	v_mfma_f32_16x16x32_bf16 v[126:129], v[86:89], v[228:231], v[126:129]
	v_mfma_f32_16x16x32_bf16 v[118:121], v[94:97], v[228:231], v[118:121]
	v_mfma_f32_16x16x32_bf16 v[106:109], v[86:89], v[236:239], v[106:109]
	v_mfma_f32_16x16x32_bf16 v[82:85], v[94:97], v[236:239], v[82:85]
	v_mfma_f32_16x16x32_bf16 v[158:161], v[90:93], v[166:169], v[158:161]
	v_mfma_f32_16x16x32_bf16 v[154:157], v[102:105], v[166:169], v[154:157]
	v_mfma_f32_16x16x32_bf16 v[142:145], v[90:93], v[224:227], v[142:145]
	v_mfma_f32_16x16x32_bf16 v[134:137], v[102:105], v[224:227], v[134:137]
	v_mfma_f32_16x16x32_bf16 v[126:129], v[90:93], v[232:235], v[126:129]
	v_mfma_f32_16x16x32_bf16 v[118:121], v[102:105], v[232:235], v[118:121]
	v_mfma_f32_16x16x32_bf16 v[106:109], v[90:93], v[240:243], v[106:109]
	v_mfma_f32_16x16x32_bf16 v[82:85], v[102:105], v[240:243], v[82:85]
	s_setprio 0
	s_barrier
	s_add_i32 s16, s18, s67
	v_lshl_add_u64 v[196:197], s[60:61], 0, v[32:33]
	s_mov_b32 m0, s16
	ds_read_b128 v[162:165], v217 offset:16384
	ds_read_b128 v[166:169], v217 offset:17408
	ds_read_b128 v[220:223], v217 offset:18432
	ds_read_b128 v[224:227], v217 offset:19456
	ds_read_b128 v[228:231], v217 offset:20480
	ds_read_b128 v[232:235], v217 offset:21504
	ds_read_b128 v[236:239], v217 offset:22528
	ds_read_b128 v[240:243], v217 offset:23552
	global_load_lds_dwordx4 v[196:197], off
	s_add_i32 m0, s16, 0x2000
	s_add_u32 s16, s60, 0x80000
	v_lshl_add_u64 v[244:245], s[60:61], 0, v[186:187]
	s_addc_u32 s17, s61, 0
	s_add_i32 s18, s19, s67
	global_load_lds_dwordx4 v[244:245], off
	v_lshl_add_u64 v[246:247], s[16:17], 0, v[32:33]
	s_mov_b32 m0, s18
	v_lshl_add_u64 v[248:249], s[62:63], 0, v[188:189]
	global_load_lds_dwordx4 v[246:247], off
	v_lshl_add_u64 v[246:247], s[16:17], 0, v[186:187]
	s_add_i32 m0, s18, 0x2000
	s_nop 0
	global_load_lds_dwordx4 v[246:247], off
	v_lshl_add_u64 v[246:247], s[62:63], 0, v[190:191]
	s_mov_b32 m0, s68
	s_nop 0
	global_load_lds_dwordx4 v[246:247], off
	s_mov_b32 m0, s14
	s_nop 0
	global_load_lds_dwordx4 v[248:249], off
	s_waitcnt vmcnt(8)
	s_waitcnt lgkmcnt(0)
	s_setprio 1
	s_barrier
; #define PG8_STAGE(bufoff, gbase, voff) do { _Pragma("unroll") for (int _i = 0; _i < 2; ++_i) \
;         __builtin_amdgcn_global_load_lds((const unsigned*)((const char*)(gbase) + (voff)[_i]), (PG8_LAS unsigned*)(lds + (bufoff) + ldsw + _i * 8192), 16, 0, 0); } while (0)
; #define PG8_LDA(dst, b, h) do { _Pragma("unroll") for (int m = 0; m < 4; ++m) _Pragma("unroll") for (int k = 0; k < 2; ++k) dst[m][k] = *(const PG8_LAS bf16x8*)(lds + PG8_SA(b, h) + aoff + m * 2048 + k * 1024); } while (0)
; #define PG8_LDB(dst, b, h) do { _Pragma("unroll") for (int n = 0; n < 2; ++n) _Pragma("unroll") for (int k = 0; k < 2; ++k) dst[n][k] = *(const PG8_LAS bf16x8*)(lds + PG8_SB(b, h) + boff + n * 2048 + k * 1024); } while (0)
; #define PG8_MMA(ai, bj, At, Bt) do { __builtin_amdgcn_s_setprio(1); _Pragma("unroll") for (int m = 0; m < 4; ++m) _Pragma("unroll") for (int n = 0; n < 2; ++n) _Pragma("unroll") for (int k = 0; k < 2; ++k) \
;         acc[ai][bj][m][n] = __builtin_amdgcn_mfma_f32_16x16x32_bf16(Bt[n][k], At[m][k], acc[ai][bj][m][n], 0, 0, 0); __builtin_amdgcn_s_setprio(0); } while (0)
; #define PG8_BAR __builtin_amdgcn_s_barrier()
; template <class Epi, class Sched, bool ALIGN_EPI = false, bool SP2 = false>
; __device__ __forceinline__ void gemm_phase(PG8_LAS unsigned char* lds, const Gemm g, const Sched& S, const Epi& E, int tid_in) {
;     ...
;             PG8_LDB(B0, 0, 0); PG8_LDB(B1, 0, 1); PG8_SCHED; PG8_LDA(At, 0, 0); PG8_STAGE(PG8_SA(1, 1), a1 + hstep, voffA);
;             PG8_WAIT_V(8); PG8_WAIT_L(0); PG8_BAR; PG8_MMA(0, 0, At, B0); PG8_MMA(0, 1, At, B1); PG8_BAR; PG8_SCHED;
;             PG8_LDA(At, 0, 1); PG8_STAGE(PG8_SB(0, 0), b2, voffB); PG8_STAGE(PG8_SB(0, 1), b2 + hstep, voffB); PG8_STAGE(PG8_SA(0, 0), a2, voffA);
;             PG8_WAIT_V(8); PG8_WAIT_L(0); PG8_BAR; PG8_MMA(1, 0, At, B0); PG8_MMA(1, 1, At, B1); PG8_BAR; PG8_SCHED;
;             PG8_LDB(B0, 1, 0); PG8_LDB(B1, 1, 1); PG8_SCHED; PG8_LDA(At, 1, 0); PG8_STAGE(PG8_SA(0, 1), a2 + hstep, voffA);
;             PG8_WAIT_V(8); PG8_WAIT_L(0); PG8_BAR; PG8_MMA(0, 0, At, B0); PG8_MMA(0, 1, At, B1); PG8_BAR; PG8_SCHED;
;             PG8_LDA(At, 1, 1); PG8_STAGE(PG8_SB(1, 0), b3, voffB); PG8_STAGE(PG8_SB(1, 1), b3 + hstep, voffB); PG8_STAGE(PG8_SA(1, 0), a3, voffA);
;             PG8_WAIT_V(8); PG8_WAIT_L(0); PG8_BAR; PG8_MMA(1, 0, At, B0); PG8_MMA(1, 1, At, B1); PG8_BAR; PG8_SCHED;
	v_mfma_f32_16x16x32_bf16 v[54:57], v[66:69], v[162:165], v[54:57]
	v_mfma_f32_16x16x32_bf16 v[50:53], v[74:77], v[162:165], v[50:53]
	v_mfma_f32_16x16x32_bf16 v[42:45], v[66:69], v[220:223], v[42:45]
	v_mfma_f32_16x16x32_bf16 v[34:37], v[74:77], v[220:223], v[34:37]
	v_mfma_f32_16x16x32_bf16 v[24:27], v[66:69], v[228:231], v[24:27]
	v_mfma_f32_16x16x32_bf16 v[12:15], v[74:77], v[228:231], v[12:15]
	v_mfma_f32_16x16x32_bf16 v[16:19], v[66:69], v[236:239], v[16:19]
	v_mfma_f32_16x16x32_bf16 v[4:7], v[74:77], v[236:239], v[4:7]
	v_mfma_f32_16x16x32_bf16 v[54:57], v[70:73], v[166:169], v[54:57]
	v_mfma_f32_16x16x32_bf16 v[50:53], v[78:81], v[166:169], v[50:53]
	v_mfma_f32_16x16x32_bf16 v[42:45], v[70:73], v[224:227], v[42:45]
	v_mfma_f32_16x16x32_bf16 v[34:37], v[78:81], v[224:227], v[34:37]
	v_mfma_f32_16x16x32_bf16 v[24:27], v[70:73], v[232:235], v[24:27]
	v_mfma_f32_16x16x32_bf16 v[12:15], v[78:81], v[232:235], v[12:15]
	v_mfma_f32_16x16x32_bf16 v[16:19], v[70:73], v[240:243], v[16:19]
	v_mfma_f32_16x16x32_bf16 v[4:7], v[78:81], v[240:243], v[4:7]
	s_setprio 0
	s_setprio 1
	v_mfma_f32_16x16x32_bf16 v[62:65], v[86:89], v[162:165], v[62:65]
	v_mfma_f32_16x16x32_bf16 v[58:61], v[94:97], v[162:165], v[58:61]
	v_mfma_f32_16x16x32_bf16 v[46:49], v[86:89], v[220:223], v[46:49]
	v_mfma_f32_16x16x32_bf16 v[38:41], v[94:97], v[220:223], v[38:41]
	v_mfma_f32_16x16x32_bf16 v[28:31], v[86:89], v[228:231], v[28:31]
	v_mfma_f32_16x16x32_bf16 v[20:23], v[94:97], v[228:231], v[20:23]
	v_mfma_f32_16x16x32_bf16 v[8:11], v[86:89], v[236:239], v[8:11]
	v_mfma_f32_16x16x32_bf16 v[0:3], v[94:97], v[236:239], v[0:3]
	v_mfma_f32_16x16x32_bf16 v[62:65], v[90:93], v[166:169], v[62:65]
	v_mfma_f32_16x16x32_bf16 v[58:61], v[102:105], v[166:169], v[58:61]
	v_mfma_f32_16x16x32_bf16 v[46:49], v[90:93], v[224:227], v[46:49]
	v_mfma_f32_16x16x32_bf16 v[38:41], v[102:105], v[224:227], v[38:41]
	v_mfma_f32_16x16x32_bf16 v[28:31], v[90:93], v[232:235], v[28:31]
	v_mfma_f32_16x16x32_bf16 v[20:23], v[102:105], v[232:235], v[20:23]
	v_mfma_f32_16x16x32_bf16 v[8:11], v[90:93], v[240:243], v[8:11]
	v_mfma_f32_16x16x32_bf16 v[0:3], v[102:105], v[240:243], v[0:3]
	s_setprio 0
	s_barrier
	s_add_i32 s18, 0, 0x18000
	s_add_i32 s19, 0, 0x1c000
	v_add_u32_e32 v78, s18, v172
	v_add_u32_e32 v102, s19, v172
	ds_read_b128 v[66:69], v78
	ds_read_b128 v[70:73], v78 offset:1024
	ds_read_b128 v[74:77], v78 offset:2048
	ds_read_b128 v[78:81], v78 offset:3072
	ds_read_b128 v[86:89], v102
	ds_read_b128 v[90:93], v102 offset:1024
	ds_read_b128 v[94:97], v102 offset:2048
	ds_read_b128 v[102:105], v102 offset:3072
	s_add_u32 s16, s62, 0x80000
	s_addc_u32 s17, s63, 0
	s_mov_b32 m0, s15
	v_lshl_add_u64 v[250:251], s[16:17], 0, v[190:191]
	ds_read_b128 v[162:165], v217 offset:32768
	ds_read_b128 v[166:169], v217 offset:33792
	ds_read_b128 v[220:223], v217 offset:34816
	ds_read_b128 v[224:227], v217 offset:35840
	ds_read_b128 v[228:231], v217 offset:36864
	ds_read_b128 v[232:235], v217 offset:37888
	ds_read_b128 v[236:239], v217 offset:38912
	ds_read_b128 v[240:243], v217 offset:39936
	global_load_lds_dwordx4 v[250:251], off
	v_lshl_add_u64 v[250:251], s[16:17], 0, v[188:189]
	s_mov_b32 m0, s4
	s_nop 0
	global_load_lds_dwordx4 v[250:251], off
	s_waitcnt vmcnt(8)
	s_waitcnt lgkmcnt(0)
	s_setprio 1
	s_barrier
	v_mfma_f32_16x16x32_bf16 v[150:153], v[66:69], v[162:165], v[150:153]
	v_mfma_f32_16x16x32_bf16 v[146:149], v[74:77], v[162:165], v[146:149]
	v_mfma_f32_16x16x32_bf16 v[138:141], v[66:69], v[220:223], v[138:141]
	v_mfma_f32_16x16x32_bf16 v[130:133], v[74:77], v[220:223], v[130:133]
	v_mfma_f32_16x16x32_bf16 v[122:125], v[66:69], v[228:231], v[122:125]
	v_mfma_f32_16x16x32_bf16 v[110:113], v[74:77], v[228:231], v[110:113]
	v_mfma_f32_16x16x32_bf16 v[114:117], v[66:69], v[236:239], v[114:117]
	v_mfma_f32_16x16x32_bf16 v[98:101], v[74:77], v[236:239], v[98:101]
	v_mfma_f32_16x16x32_bf16 v[150:153], v[70:73], v[166:169], v[150:153]
	v_mfma_f32_16x16x32_bf16 v[146:149], v[78:81], v[166:169], v[146:149]
	v_mfma_f32_16x16x32_bf16 v[138:141], v[70:73], v[224:227], v[138:141]
	v_mfma_f32_16x16x32_bf16 v[130:133], v[78:81], v[224:227], v[130:133]
	v_mfma_f32_16x16x32_bf16 v[122:125], v[70:73], v[232:235], v[122:125]
	v_mfma_f32_16x16x32_bf16 v[110:113], v[78:81], v[232:235], v[110:113]
	v_mfma_f32_16x16x32_bf16 v[114:117], v[70:73], v[240:243], v[114:117]
	v_mfma_f32_16x16x32_bf16 v[98:101], v[78:81], v[240:243], v[98:101]
	s_setprio 0
	s_setprio 1
	v_mfma_f32_16x16x32_bf16 v[158:161], v[86:89], v[162:165], v[158:161]
	v_mfma_f32_16x16x32_bf16 v[154:157], v[94:97], v[162:165], v[154:157]
	v_mfma_f32_16x16x32_bf16 v[142:145], v[86:89], v[220:223], v[142:145]
	v_mfma_f32_16x16x32_bf16 v[134:137], v[94:97], v[220:223], v[134:137]
	v_mfma_f32_16x16x32_bf16 v[126:129], v[86:89], v[228:231], v[126:129]
	v_mfma_f32_16x16x32_bf16 v[118:121], v[94:97], v[228:231], v[118:121]
	v_mfma_f32_16x16x32_bf16 v[106:109], v[86:89], v[236:239], v[106:109]
	v_mfma_f32_16x16x32_bf16 v[82:85], v[94:97], v[236:239], v[82:85]
	v_mfma_f32_16x16x32_bf16 v[158:161], v[90:93], v[166:169], v[158:161]
	v_mfma_f32_16x16x32_bf16 v[154:157], v[102:105], v[166:169], v[154:157]
	v_mfma_f32_16x16x32_bf16 v[142:145], v[90:93], v[224:227], v[142:145]
	v_mfma_f32_16x16x32_bf16 v[134:137], v[102:105], v[224:227], v[134:137]
	v_mfma_f32_16x16x32_bf16 v[126:129], v[90:93], v[232:235], v[126:129]
	v_mfma_f32_16x16x32_bf16 v[118:121], v[102:105], v[232:235], v[118:121]
	v_mfma_f32_16x16x32_bf16 v[106:109], v[90:93], v[240:243], v[106:109]
	v_mfma_f32_16x16x32_bf16 v[82:85], v[102:105], v[240:243], v[82:85]
	s_setprio 0
	s_barrier
; #define PG8_STAGE(bufoff, gbase, voff) do { _Pragma("unroll") for (int _i = 0; _i < 2; ++_i) \
;         __builtin_amdgcn_global_load_lds((const unsigned*)((const char*)(gbase) + (voff)[_i]), (PG8_LAS unsigned*)(lds + (bufoff) + ldsw + _i * 8192), 16, 0, 0); } while (0)
; #define PG8_LDA(dst, b, h) do { _Pragma("unroll") for (int m = 0; m < 4; ++m) _Pragma("unroll") for (int k = 0; k < 2; ++k) dst[m][k] = *(const PG8_LAS bf16x8*)(lds + PG8_SA(b, h) + aoff + m * 2048 + k * 1024); } while (0)
; #define PG8_LDB(dst, b, h) do { _Pragma("unroll") for (int n = 0; n < 2; ++n) _Pragma("unroll") for (int k = 0; k < 2; ++k) dst[n][k] = *(const PG8_LAS bf16x8*)(lds + PG8_SB(b, h) + boff + n * 2048 + k * 1024); } while (0)
; #define PG8_MMA(ai, bj, At, Bt) do { __builtin_amdgcn_s_setprio(1); _Pragma("unroll") for (int m = 0; m < 4; ++m) _Pragma("unroll") for (int n = 0; n < 2; ++n) _Pragma("unroll") for (int k = 0; k < 2; ++k) \
;         acc[ai][bj][m][n] = __builtin_amdgcn_mfma_f32_16x16x32_bf16(Bt[n][k], At[m][k], acc[ai][bj][m][n], 0, 0, 0); __builtin_amdgcn_s_setprio(0); } while (0)
; #define PG8_BAR __builtin_amdgcn_s_barrier()
; template <class Epi, class Sched, bool ALIGN_EPI = false, bool SP2 = false>
; __device__ __forceinline__ void gemm_phase(PG8_LAS unsigned char* lds, const Gemm g, const Sched& S, const Epi& E, int tid_in) {
;     ...
;             PG8_LDB(B0, 0, 0); PG8_LDB(B1, 0, 1); PG8_SCHED; PG8_LDA(At, 0, 0); PG8_STAGE(PG8_SA(1, 1), a1 + hstep, voffA);
;             PG8_WAIT_V(8); PG8_WAIT_L(0); PG8_BAR; PG8_MMA(0, 0, At, B0); PG8_MMA(0, 1, At, B1); PG8_BAR; PG8_SCHED;
;             PG8_LDA(At, 0, 1); PG8_STAGE(PG8_SB(0, 0), b2, voffB); PG8_STAGE(PG8_SB(0, 1), b2 + hstep, voffB); PG8_STAGE(PG8_SA(0, 0), a2, voffA);
;             PG8_WAIT_V(8); PG8_WAIT_L(0); PG8_BAR; PG8_MMA(1, 0, At, B0); PG8_MMA(1, 1, At, B1); PG8_BAR; PG8_SCHED;
;             PG8_LDB(B0, 1, 0); PG8_LDB(B1, 1, 1); PG8_SCHED; PG8_LDA(At, 1, 0); PG8_STAGE(PG8_SA(0, 1), a2 + hstep, voffA);
;             PG8_WAIT_V(8); PG8_WAIT_L(0); PG8_BAR; PG8_MMA(0, 0, At, B0); PG8_MMA(0, 1, At, B1); PG8_BAR; PG8_SCHED;
;             PG8_LDA(At, 1, 1); PG8_STAGE(PG8_SB(1, 0), b3, voffB); PG8_STAGE(PG8_SB(1, 1), b3 + hstep, voffB); PG8_STAGE(PG8_SA(1, 0), a3, voffA);
;             PG8_WAIT_V(8); PG8_WAIT_L(0); PG8_BAR; PG8_MMA(1, 0, At, B0); PG8_MMA(1, 1, At, B1); PG8_BAR; PG8_SCHED;
	s_add_i32 s16, s18, s67
	v_lshl_add_u64 v[196:197], v[196:197], 0, s[74:75]
	s_mov_b32 m0, s16
	ds_read_b128 v[162:165], v217 offset:49152
	ds_read_b128 v[166:169], v217 offset:50176
	ds_read_b128 v[220:223], v217 offset:51200
	ds_read_b128 v[224:227], v217 offset:52224
	ds_read_b128 v[228:231], v217 offset:53248
	ds_read_b128 v[232:235], v217 offset:54272
	ds_read_b128 v[236:239], v217 offset:55296
	ds_read_b128 v[240:243], v217 offset:56320
	global_load_lds_dwordx4 v[196:197], off
	s_add_i32 m0, s16, 0x2000
	s_add_u32 s16, s60, 0x80080
	v_lshl_add_u64 v[196:197], v[244:245], 0, s[74:75]
	s_addc_u32 s17, s61, 0
	s_add_i32 s18, s19, s67
	global_load_lds_dwordx4 v[196:197], off
	v_lshl_add_u64 v[196:197], s[16:17], 0, v[32:33]
	s_mov_b32 m0, s18
	s_nop 0
	global_load_lds_dwordx4 v[196:197], off
	v_lshl_add_u64 v[196:197], s[16:17], 0, v[186:187]
	s_add_i32 m0, s18, 0x2000
	s_nop 0
	global_load_lds_dwordx4 v[196:197], off
	v_lshl_add_u64 v[196:197], v[246:247], 0, s[74:75]
	s_mov_b32 m0, s85
	s_nop 0
	global_load_lds_dwordx4 v[196:197], off
	v_lshl_add_u64 v[196:197], v[248:249], 0, s[74:75]
	s_mov_b32 m0, s80
	s_nop 0
	global_load_lds_dwordx4 v[196:197], off
	s_waitcnt vmcnt(8)
	s_waitcnt lgkmcnt(0)
	s_setprio 1
	s_barrier
	v_mfma_f32_16x16x32_bf16 v[54:57], v[66:69], v[162:165], v[54:57]
	v_mfma_f32_16x16x32_bf16 v[50:53], v[74:77], v[162:165], v[50:53]
	v_mfma_f32_16x16x32_bf16 v[42:45], v[66:69], v[220:223], v[42:45]
	v_mfma_f32_16x16x32_bf16 v[34:37], v[74:77], v[220:223], v[34:37]
	v_mfma_f32_16x16x32_bf16 v[24:27], v[66:69], v[228:231], v[24:27]
	v_mfma_f32_16x16x32_bf16 v[12:15], v[74:77], v[228:231], v[12:15]
	v_mfma_f32_16x16x32_bf16 v[16:19], v[66:69], v[236:239], v[16:19]
	v_mfma_f32_16x16x32_bf16 v[4:7], v[74:77], v[236:239], v[4:7]
	v_mfma_f32_16x16x32_bf16 v[54:57], v[70:73], v[166:169], v[54:57]
	v_mfma_f32_16x16x32_bf16 v[50:53], v[78:81], v[166:169], v[50:53]
	v_mfma_f32_16x16x32_bf16 v[42:45], v[70:73], v[224:227], v[42:45]
	v_mfma_f32_16x16x32_bf16 v[34:37], v[78:81], v[224:227], v[34:37]
	v_mfma_f32_16x16x32_bf16 v[24:27], v[70:73], v[232:235], v[24:27]
	v_mfma_f32_16x16x32_bf16 v[12:15], v[78:81], v[232:235], v[12:15]
	v_mfma_f32_16x16x32_bf16 v[16:19], v[70:73], v[240:243], v[16:19]
	v_mfma_f32_16x16x32_bf16 v[4:7], v[78:81], v[240:243], v[4:7]
	s_setprio 0
	s_setprio 1
	v_mfma_f32_16x16x32_bf16 v[62:65], v[86:89], v[162:165], v[62:65]
	v_mfma_f32_16x16x32_bf16 v[58:61], v[94:97], v[162:165], v[58:61]
	v_mfma_f32_16x16x32_bf16 v[46:49], v[86:89], v[220:223], v[46:49]
	v_mfma_f32_16x16x32_bf16 v[38:41], v[94:97], v[220:223], v[38:41]
	v_mfma_f32_16x16x32_bf16 v[28:31], v[86:89], v[228:231], v[28:31]
	v_mfma_f32_16x16x32_bf16 v[20:23], v[94:97], v[228:231], v[20:23]
	v_mfma_f32_16x16x32_bf16 v[8:11], v[86:89], v[236:239], v[8:11]
	v_mfma_f32_16x16x32_bf16 v[0:3], v[94:97], v[236:239], v[0:3]
	v_mfma_f32_16x16x32_bf16 v[62:65], v[90:93], v[166:169], v[62:65]
	v_mfma_f32_16x16x32_bf16 v[58:61], v[102:105], v[166:169], v[58:61]
	v_mfma_f32_16x16x32_bf16 v[46:49], v[90:93], v[224:227], v[46:49]
	v_mfma_f32_16x16x32_bf16 v[38:41], v[102:105], v[224:227], v[38:41]
	v_mfma_f32_16x16x32_bf16 v[28:31], v[90:93], v[232:235], v[28:31]
	v_mfma_f32_16x16x32_bf16 v[20:23], v[102:105], v[232:235], v[20:23]
	v_mfma_f32_16x16x32_bf16 v[8:11], v[90:93], v[240:243], v[8:11]
	v_mfma_f32_16x16x32_bf16 v[0:3], v[102:105], v[240:243], v[0:3]
	s_setprio 0
	s_barrier
	s_add_i32 s82, s82, 2
	s_add_u32 s56, s56, 0x100
	s_addc_u32 s57, s57, 0
	s_add_u32 s47, s47, 0x100
	s_addc_u32 s77, s77, 0
	s_cmp_gt_u32 s82, 29
	s_cbranch_scc0 .LBB0_479
	s_and_b64 vcc, exec, s[34:35]
	s_cbranch_vccz .LBB0_482
	s_barrier

; #define PG8_STAGE(bufoff, gbase, voff) do { _Pragma("unroll") for (int _i = 0; _i < 2; ++_i) \
;         __builtin_amdgcn_global_load_lds((const unsigned*)((const char*)(gbase) + (voff)[_i]), (PG8_LAS unsigned*)(lds + (bufoff) + ldsw + _i * 8192), 16, 0, 0); } while (0)
; #define PG8_LDA(dst, b, h) do { _Pragma("unroll") for (int m = 0; m < 4; ++m) _Pragma("unroll") for (int k = 0; k < 2; ++k) dst[m][k] = *(const PG8_LAS bf16x8*)(lds + PG8_SA(b, h) + aoff + m * 2048 + k * 1024); } while (0)
; #define PG8_LDB(dst, b, h) do { _Pragma("unroll") for (int n = 0; n < 2; ++n) _Pragma("unroll") for (int k = 0; k < 2; ++k) dst[n][k] = *(const PG8_LAS bf16x8*)(lds + PG8_SB(b, h) + boff + n * 2048 + k * 1024); } while (0)
; #define PG8_MMA(ai, bj, At, Bt) do { __builtin_amdgcn_s_setprio(1); _Pragma("unroll") for (int m = 0; m < 4; ++m) _Pragma("unroll") for (int n = 0; n < 2; ++n) _Pragma("unroll") for (int k = 0; k < 2; ++k) \
;         acc[ai][bj][m][n] = __builtin_amdgcn_mfma_f32_16x16x32_bf16(Bt[n][k], At[m][k], acc[ai][bj][m][n], 0, 0, 0); __builtin_amdgcn_s_setprio(0); } while (0)
; #define PG8_BAR __builtin_amdgcn_s_barrier()
; template <class Epi, class Sched, bool ALIGN_EPI = false, bool SP2 = false>
; __device__ __forceinline__ void gemm_phase(PG8_LAS unsigned char* lds, const Gemm g, const Sched& S, const Epi& E, int tid_in) {
;     ...
;             PG8_LDB(B0, 0, 0); PG8_LDB(B1, 0, 1); PG8_SCHED; PG8_LDA(At, 0, 0); PG8_STAGE(PG8_SA(1, 1), a1 + hstep, voffA);
;             PG8_WAIT_V(8); PG8_WAIT_L(0); PG8_BAR; PG8_MMA(0, 0, At, B0); PG8_MMA(0, 1, At, B1); PG8_BAR; PG8_SCHED;
;             PG8_LDA(At, 0, 1); PG8_STAGE(PG8_SB(0, 0), b2, voffB); PG8_STAGE(PG8_SB(0, 1), b2 + hstep, voffB); PG8_STAGE(PG8_SA(0, 0), a2, voffA);
;             PG8_WAIT_V(8); PG8_WAIT_L(0); PG8_BAR; PG8_MMA(1, 0, At, B0); PG8_MMA(1, 1, At, B1); PG8_BAR; PG8_SCHED;
;             PG8_LDB(B0, 1, 0); PG8_LDB(B1, 1, 1); PG8_SCHED; PG8_LDA(At, 1, 0); PG8_STAGE(PG8_SA(0, 1), a2 + hstep, voffA);
;             PG8_WAIT_V(8); PG8_WAIT_L(0); PG8_BAR; PG8_MMA(0, 0, At, B0); PG8_MMA(0, 1, At, B1); PG8_BAR; PG8_SCHED;
;             PG8_LDA(At, 1, 1); PG8_STAGE(PG8_SB(1, 0), b3, voffB); PG8_STAGE(PG8_SB(1, 1), b3 + hstep, voffB); PG8_STAGE(PG8_SA(1, 0), a3, voffA);
;             PG8_WAIT_V(8); PG8_WAIT_L(0); PG8_BAR; PG8_MMA(1, 0, At, B0); PG8_MMA(1, 1, At, B1); PG8_BAR; PG8_SCHED;
.LBB0_625:
	s_add_u32 s26, s24, 0x100
	s_addc_u32 s27, s25, 0
	s_add_i32 s58, 0, 0x10000
	s_cmpk_eq_i32 s57, 0x54
	s_cselect_b32 s31, s7, s27
	s_cselect_b32 s30, s6, s26
	s_cselect_b32 s29, s23, s47
	s_cselect_b32 s28, s22, s45
	s_add_i32 s59, 0, 0x14000
	v_add_u32_e32 v152, s58, v141
	v_add_u32_e32 v168, s59, v141
	ds_read_b128 v[136:139], v152
	ds_read_b128 v[144:147], v152 offset:1024
	ds_read_b128 v[148:151], v152 offset:2048
	ds_read_b128 v[152:155], v152 offset:3072
	ds_read_b128 v[156:159], v168
	ds_read_b128 v[160:163], v168 offset:1024
	ds_read_b128 v[164:167], v168 offset:2048
	ds_read_b128 v[186:189], v168 offset:3072
	v_lshl_add_u64 v[168:169], s[24:25], 0, v[132:133]
	s_add_i32 m0, s38, 0xc000
	ds_read_b128 v[190:193], v143
	ds_read_b128 v[194:197], v143 offset:1024
	ds_read_b128 v[212:215], v143 offset:2048
	ds_read_b128 v[220:223], v143 offset:3072
	ds_read_b128 v[224:227], v143 offset:4096
	ds_read_b128 v[228:231], v143 offset:5120
	ds_read_b128 v[232:235], v143 offset:6144
	ds_read_b128 v[236:239], v143 offset:7168
	global_load_lds_dwordx4 v[168:169], off
	v_lshl_add_u64 v[168:169], s[24:25], 0, v[134:135]
	s_add_i32 m0, s38, 0xe000
	s_nop 0
	global_load_lds_dwordx4 v[168:169], off
	s_waitcnt vmcnt(8)
	s_waitcnt lgkmcnt(0)
	s_setprio 1
	s_barrier
	v_mfma_f32_16x16x32_bf16 v[126:129], v[136:139], v[190:193], v[126:129]
	v_mfma_f32_16x16x32_bf16 v[122:125], v[148:151], v[190:193], v[122:125]
	v_mfma_f32_16x16x32_bf16 v[114:117], v[136:139], v[212:215], v[114:117]
	v_mfma_f32_16x16x32_bf16 v[110:113], v[148:151], v[212:215], v[110:113]
	v_mfma_f32_16x16x32_bf16 v[98:101], v[136:139], v[224:227], v[98:101]
	v_mfma_f32_16x16x32_bf16 v[94:97], v[148:151], v[224:227], v[94:97]
	v_mfma_f32_16x16x32_bf16 v[82:85], v[136:139], v[232:235], v[82:85]
	v_mfma_f32_16x16x32_bf16 v[78:81], v[148:151], v[232:235], v[78:81]
	v_mfma_f32_16x16x32_bf16 v[126:129], v[144:147], v[194:197], v[126:129]
	v_mfma_f32_16x16x32_bf16 v[122:125], v[152:155], v[194:197], v[122:125]
	v_mfma_f32_16x16x32_bf16 v[114:117], v[144:147], v[220:223], v[114:117]
	v_mfma_f32_16x16x32_bf16 v[110:113], v[152:155], v[220:223], v[110:113]
	v_mfma_f32_16x16x32_bf16 v[98:101], v[144:147], v[228:231], v[98:101]
	v_mfma_f32_16x16x32_bf16 v[94:97], v[152:155], v[228:231], v[94:97]
	v_mfma_f32_16x16x32_bf16 v[82:85], v[144:147], v[236:239], v[82:85]
	v_mfma_f32_16x16x32_bf16 v[78:81], v[152:155], v[236:239], v[78:81]
	s_setprio 0
	s_setprio 1
	v_mfma_f32_16x16x32_bf16 v[118:121], v[156:159], v[190:193], v[118:121]
	v_mfma_f32_16x16x32_bf16 v[106:109], v[164:167], v[190:193], v[106:109]
	v_mfma_f32_16x16x32_bf16 v[102:105], v[156:159], v[212:215], v[102:105]
	v_mfma_f32_16x16x32_bf16 v[90:93], v[164:167], v[212:215], v[90:93]
	v_mfma_f32_16x16x32_bf16 v[86:89], v[156:159], v[224:227], v[86:89]
	v_mfma_f32_16x16x32_bf16 v[74:77], v[164:167], v[224:227], v[74:77]
	v_mfma_f32_16x16x32_bf16 v[70:73], v[156:159], v[232:235], v[70:73]
	v_mfma_f32_16x16x32_bf16 v[66:69], v[164:167], v[232:235], v[66:69]
	v_mfma_f32_16x16x32_bf16 v[118:121], v[160:163], v[194:197], v[118:121]
	v_mfma_f32_16x16x32_bf16 v[106:109], v[186:189], v[194:197], v[106:109]
	v_mfma_f32_16x16x32_bf16 v[102:105], v[160:163], v[220:223], v[102:105]
	v_mfma_f32_16x16x32_bf16 v[90:93], v[186:189], v[220:223], v[90:93]
	v_mfma_f32_16x16x32_bf16 v[86:89], v[160:163], v[228:231], v[86:89]
	v_mfma_f32_16x16x32_bf16 v[74:77], v[186:189], v[228:231], v[74:77]
	v_mfma_f32_16x16x32_bf16 v[70:73], v[160:163], v[236:239], v[70:73]
	v_mfma_f32_16x16x32_bf16 v[66:69], v[186:189], v[236:239], v[66:69]
	s_setprio 0
	s_barrier
	s_add_i32 s24, s58, s35
	v_lshl_add_u64 v[168:169], s[28:29], 0, v[32:33]
	s_mov_b32 m0, s24
	ds_read_b128 v[190:193], v143 offset:16384
	ds_read_b128 v[194:197], v143 offset:17408
	ds_read_b128 v[212:215], v143 offset:18432
	ds_read_b128 v[220:223], v143 offset:19456
	ds_read_b128 v[224:227], v143 offset:20480
	ds_read_b128 v[228:231], v143 offset:21504
	ds_read_b128 v[232:235], v143 offset:22528
	ds_read_b128 v[236:239], v143 offset:23552
	global_load_lds_dwordx4 v[168:169], off
	s_add_i32 m0, s24, 0x2000
	s_add_u32 s24, s28, 0x160000
	v_lshl_add_u64 v[216:217], s[28:29], 0, v[130:131]
	s_addc_u32 s25, s29, 0
	s_add_i32 s58, s59, s35
	global_load_lds_dwordx4 v[216:217], off
	v_lshl_add_u64 v[240:241], s[24:25], 0, v[32:33]
	s_mov_b32 m0, s58
	v_lshl_add_u64 v[242:243], s[30:31], 0, v[130:131]
	global_load_lds_dwordx4 v[240:241], off
	v_lshl_add_u64 v[240:241], s[24:25], 0, v[130:131]
	s_add_i32 m0, s58, 0x2000
	s_nop 0
	global_load_lds_dwordx4 v[240:241], off
	v_lshl_add_u64 v[240:241], s[30:31], 0, v[32:33]
	s_mov_b32 m0, s38
	s_nop 0
	global_load_lds_dwordx4 v[240:241], off
	s_mov_b32 m0, s39
	s_nop 0
	global_load_lds_dwordx4 v[242:243], off
	s_waitcnt vmcnt(8)
	s_waitcnt lgkmcnt(0)
	s_setprio 1
	s_barrier
; #define PG8_STAGE(bufoff, gbase, voff) do { _Pragma("unroll") for (int _i = 0; _i < 2; ++_i) \
;         __builtin_amdgcn_global_load_lds((const unsigned*)((const char*)(gbase) + (voff)[_i]), (PG8_LAS unsigned*)(lds + (bufoff) + ldsw + _i * 8192), 16, 0, 0); } while (0)
; #define PG8_LDA(dst, b, h) do { _Pragma("unroll") for (int m = 0; m < 4; ++m) _Pragma("unroll") for (int k = 0; k < 2; ++k) dst[m][k] = *(const PG8_LAS bf16x8*)(lds + PG8_SA(b, h) + aoff + m * 2048 + k * 1024); } while (0)
; #define PG8_LDB(dst, b, h) do { _Pragma("unroll") for (int n = 0; n < 2; ++n) _Pragma("unroll") for (int k = 0; k < 2; ++k) dst[n][k] = *(const PG8_LAS bf16x8*)(lds + PG8_SB(b, h) + boff + n * 2048 + k * 1024); } while (0)
; #define PG8_MMA(ai, bj, At, Bt) do { __builtin_amdgcn_s_setprio(1); _Pragma("unroll") for (int m = 0; m < 4; ++m) _Pragma("unroll") for (int n = 0; n < 2; ++n) _Pragma("unroll") for (int k = 0; k < 2; ++k) \
;         acc[ai][bj][m][n] = __builtin_amdgcn_mfma_f32_16x16x32_bf16(Bt[n][k], At[m][k], acc[ai][bj][m][n], 0, 0, 0); __builtin_amdgcn_s_setprio(0); } while (0)
; #define PG8_BAR __builtin_amdgcn_s_barrier()
; template <class Epi, class Sched, bool ALIGN_EPI = false, bool SP2 = false>
; __device__ __forceinline__ void gemm_phase(PG8_LAS unsigned char* lds, const Gemm g, const Sched& S, const Epi& E, int tid_in) {
;     ...
;             PG8_LDB(B0, 0, 0); PG8_LDB(B1, 0, 1); PG8_SCHED; PG8_LDA(At, 0, 0); PG8_STAGE(PG8_SA(1, 1), a1 + hstep, voffA);
;             PG8_WAIT_V(8); PG8_WAIT_L(0); PG8_BAR; PG8_MMA(0, 0, At, B0); PG8_MMA(0, 1, At, B1); PG8_BAR; PG8_SCHED;
;             PG8_LDA(At, 0, 1); PG8_STAGE(PG8_SB(0, 0), b2, voffB); PG8_STAGE(PG8_SB(0, 1), b2 + hstep, voffB); PG8_STAGE(PG8_SA(0, 0), a2, voffA);
;             PG8_WAIT_V(8); PG8_WAIT_L(0); PG8_BAR; PG8_MMA(1, 0, At, B0); PG8_MMA(1, 1, At, B1); PG8_BAR; PG8_SCHED;
;             PG8_LDB(B0, 1, 0); PG8_LDB(B1, 1, 1); PG8_SCHED; PG8_LDA(At, 1, 0); PG8_STAGE(PG8_SA(0, 1), a2 + hstep, voffA);
;             PG8_WAIT_V(8); PG8_WAIT_L(0); PG8_BAR; PG8_MMA(0, 0, At, B0); PG8_MMA(0, 1, At, B1); PG8_BAR; PG8_SCHED;
;             PG8_LDA(At, 1, 1); PG8_STAGE(PG8_SB(1, 0), b3, voffB); PG8_STAGE(PG8_SB(1, 1), b3 + hstep, voffB); PG8_STAGE(PG8_SA(1, 0), a3, voffA);
;             PG8_WAIT_V(8); PG8_WAIT_L(0); PG8_BAR; PG8_MMA(1, 0, At, B0); PG8_MMA(1, 1, At, B1); PG8_BAR; PG8_SCHED;
	v_mfma_f32_16x16x32_bf16 v[62:65], v[136:139], v[190:193], v[62:65]
	v_mfma_f32_16x16x32_bf16 v[58:61], v[148:151], v[190:193], v[58:61]
	v_mfma_f32_16x16x32_bf16 v[50:53], v[136:139], v[212:215], v[50:53]
	v_mfma_f32_16x16x32_bf16 v[46:49], v[148:151], v[212:215], v[46:49]
	v_mfma_f32_16x16x32_bf16 v[34:37], v[136:139], v[224:227], v[34:37]
	v_mfma_f32_16x16x32_bf16 v[28:31], v[148:151], v[224:227], v[28:31]
	v_mfma_f32_16x16x32_bf16 v[16:19], v[136:139], v[232:235], v[16:19]
	v_mfma_f32_16x16x32_bf16 v[12:15], v[148:151], v[232:235], v[12:15]
	v_mfma_f32_16x16x32_bf16 v[62:65], v[144:147], v[194:197], v[62:65]
	v_mfma_f32_16x16x32_bf16 v[58:61], v[152:155], v[194:197], v[58:61]
	v_mfma_f32_16x16x32_bf16 v[50:53], v[144:147], v[220:223], v[50:53]
	v_mfma_f32_16x16x32_bf16 v[46:49], v[152:155], v[220:223], v[46:49]
	v_mfma_f32_16x16x32_bf16 v[34:37], v[144:147], v[228:231], v[34:37]
	v_mfma_f32_16x16x32_bf16 v[28:31], v[152:155], v[228:231], v[28:31]
	v_mfma_f32_16x16x32_bf16 v[16:19], v[144:147], v[236:239], v[16:19]
	v_mfma_f32_16x16x32_bf16 v[12:15], v[152:155], v[236:239], v[12:15]
	s_setprio 0
	s_setprio 1
	v_mfma_f32_16x16x32_bf16 v[54:57], v[156:159], v[190:193], v[54:57]
	v_mfma_f32_16x16x32_bf16 v[42:45], v[164:167], v[190:193], v[42:45]
	v_mfma_f32_16x16x32_bf16 v[38:41], v[156:159], v[212:215], v[38:41]
	v_mfma_f32_16x16x32_bf16 v[24:27], v[164:167], v[212:215], v[24:27]
	v_mfma_f32_16x16x32_bf16 v[20:23], v[156:159], v[224:227], v[20:23]
	v_mfma_f32_16x16x32_bf16 v[8:11], v[164:167], v[224:227], v[8:11]
	v_mfma_f32_16x16x32_bf16 v[4:7], v[156:159], v[232:235], v[4:7]
	v_mfma_f32_16x16x32_bf16 v[0:3], v[164:167], v[232:235], v[0:3]
	v_mfma_f32_16x16x32_bf16 v[54:57], v[160:163], v[194:197], v[54:57]
	v_mfma_f32_16x16x32_bf16 v[42:45], v[186:189], v[194:197], v[42:45]
	v_mfma_f32_16x16x32_bf16 v[38:41], v[160:163], v[220:223], v[38:41]
	v_mfma_f32_16x16x32_bf16 v[24:27], v[186:189], v[220:223], v[24:27]
	v_mfma_f32_16x16x32_bf16 v[20:23], v[160:163], v[228:231], v[20:23]
	v_mfma_f32_16x16x32_bf16 v[8:11], v[186:189], v[228:231], v[8:11]
	v_mfma_f32_16x16x32_bf16 v[4:7], v[160:163], v[236:239], v[4:7]
	v_mfma_f32_16x16x32_bf16 v[0:3], v[186:189], v[236:239], v[0:3]
	s_setprio 0
	s_barrier
	s_add_i32 s58, 0, 0x18000
	s_add_i32 s59, 0, 0x1c000
	v_add_u32_e32 v152, s58, v141
	v_add_u32_e32 v170, s59, v141
	ds_read_b128 v[136:139], v152
	ds_read_b128 v[144:147], v152 offset:1024
	ds_read_b128 v[148:151], v152 offset:2048
	ds_read_b128 v[152:155], v152 offset:3072
	ds_read_b128 v[156:159], v170
	ds_read_b128 v[160:163], v170 offset:1024
	ds_read_b128 v[164:167], v170 offset:2048
	ds_read_b128 v[186:189], v170 offset:3072
	s_add_u32 s24, s30, 0x160000
	s_addc_u32 s25, s31, 0
	s_mov_b32 m0, s42
	v_lshl_add_u64 v[244:245], s[24:25], 0, v[32:33]
	ds_read_b128 v[190:193], v143 offset:32768
	ds_read_b128 v[194:197], v143 offset:33792
	ds_read_b128 v[212:215], v143 offset:34816
	ds_read_b128 v[220:223], v143 offset:35840
	ds_read_b128 v[224:227], v143 offset:36864
	ds_read_b128 v[228:231], v143 offset:37888
	ds_read_b128 v[232:235], v143 offset:38912
	ds_read_b128 v[236:239], v143 offset:39936
	global_load_lds_dwordx4 v[244:245], off
	v_lshl_add_u64 v[244:245], s[24:25], 0, v[130:131]
	s_mov_b32 m0, s43
	s_nop 0
	global_load_lds_dwordx4 v[244:245], off
	s_waitcnt vmcnt(8)
	s_waitcnt lgkmcnt(0)
	s_setprio 1
	s_barrier
	v_mfma_f32_16x16x32_bf16 v[126:129], v[136:139], v[190:193], v[126:129]
	v_mfma_f32_16x16x32_bf16 v[122:125], v[148:151], v[190:193], v[122:125]
	v_mfma_f32_16x16x32_bf16 v[114:117], v[136:139], v[212:215], v[114:117]
	v_mfma_f32_16x16x32_bf16 v[110:113], v[148:151], v[212:215], v[110:113]
	v_mfma_f32_16x16x32_bf16 v[98:101], v[136:139], v[224:227], v[98:101]
	v_mfma_f32_16x16x32_bf16 v[94:97], v[148:151], v[224:227], v[94:97]
	v_mfma_f32_16x16x32_bf16 v[82:85], v[136:139], v[232:235], v[82:85]
	v_mfma_f32_16x16x32_bf16 v[78:81], v[148:151], v[232:235], v[78:81]
	v_mfma_f32_16x16x32_bf16 v[126:129], v[144:147], v[194:197], v[126:129]
	v_mfma_f32_16x16x32_bf16 v[122:125], v[152:155], v[194:197], v[122:125]
	v_mfma_f32_16x16x32_bf16 v[114:117], v[144:147], v[220:223], v[114:117]
	v_mfma_f32_16x16x32_bf16 v[110:113], v[152:155], v[220:223], v[110:113]
	v_mfma_f32_16x16x32_bf16 v[98:101], v[144:147], v[228:231], v[98:101]
	v_mfma_f32_16x16x32_bf16 v[94:97], v[152:155], v[228:231], v[94:97]
	v_mfma_f32_16x16x32_bf16 v[82:85], v[144:147], v[236:239], v[82:85]
	v_mfma_f32_16x16x32_bf16 v[78:81], v[152:155], v[236:239], v[78:81]
	s_setprio 0
	s_setprio 1
	v_mfma_f32_16x16x32_bf16 v[118:121], v[156:159], v[190:193], v[118:121]
	v_mfma_f32_16x16x32_bf16 v[106:109], v[164:167], v[190:193], v[106:109]
	v_mfma_f32_16x16x32_bf16 v[102:105], v[156:159], v[212:215], v[102:105]
	v_mfma_f32_16x16x32_bf16 v[90:93], v[164:167], v[212:215], v[90:93]
	v_mfma_f32_16x16x32_bf16 v[86:89], v[156:159], v[224:227], v[86:89]
	v_mfma_f32_16x16x32_bf16 v[74:77], v[164:167], v[224:227], v[74:77]
	v_mfma_f32_16x16x32_bf16 v[70:73], v[156:159], v[232:235], v[70:73]
	v_mfma_f32_16x16x32_bf16 v[66:69], v[164:167], v[232:235], v[66:69]
	v_mfma_f32_16x16x32_bf16 v[118:121], v[160:163], v[194:197], v[118:121]
	v_mfma_f32_16x16x32_bf16 v[106:109], v[186:189], v[194:197], v[106:109]
	v_mfma_f32_16x16x32_bf16 v[102:105], v[160:163], v[220:223], v[102:105]
	v_mfma_f32_16x16x32_bf16 v[90:93], v[186:189], v[220:223], v[90:93]
	v_mfma_f32_16x16x32_bf16 v[86:89], v[160:163], v[228:231], v[86:89]
	v_mfma_f32_16x16x32_bf16 v[74:77], v[186:189], v[228:231], v[74:77]
	v_mfma_f32_16x16x32_bf16 v[70:73], v[160:163], v[236:239], v[70:73]
	v_mfma_f32_16x16x32_bf16 v[66:69], v[186:189], v[236:239], v[66:69]
	s_setprio 0
	s_barrier
; #define PG8_STAGE(bufoff, gbase, voff) do { _Pragma("unroll") for (int _i = 0; _i < 2; ++_i) \
;         __builtin_amdgcn_global_load_lds((const unsigned*)((const char*)(gbase) + (voff)[_i]), (PG8_LAS unsigned*)(lds + (bufoff) + ldsw + _i * 8192), 16, 0, 0); } while (0)
; #define PG8_LDA(dst, b, h) do { _Pragma("unroll") for (int m = 0; m < 4; ++m) _Pragma("unroll") for (int k = 0; k < 2; ++k) dst[m][k] = *(const PG8_LAS bf16x8*)(lds + PG8_SA(b, h) + aoff + m * 2048 + k * 1024); } while (0)
; #define PG8_LDB(dst, b, h) do { _Pragma("unroll") for (int n = 0; n < 2; ++n) _Pragma("unroll") for (int k = 0; k < 2; ++k) dst[n][k] = *(const PG8_LAS bf16x8*)(lds + PG8_SB(b, h) + boff + n * 2048 + k * 1024); } while (0)
; #define PG8_MMA(ai, bj, At, Bt) do { __builtin_amdgcn_s_setprio(1); _Pragma("unroll") for (int m = 0; m < 4; ++m) _Pragma("unroll") for (int n = 0; n < 2; ++n) _Pragma("unroll") for (int k = 0; k < 2; ++k) \
;         acc[ai][bj][m][n] = __builtin_amdgcn_mfma_f32_16x16x32_bf16(Bt[n][k], At[m][k], acc[ai][bj][m][n], 0, 0, 0); __builtin_amdgcn_s_setprio(0); } while (0)
; #define PG8_BAR __builtin_amdgcn_s_barrier()
; template <class Epi, class Sched, bool ALIGN_EPI = false, bool SP2 = false>
; __device__ __forceinline__ void gemm_phase(PG8_LAS unsigned char* lds, const Gemm g, const Sched& S, const Epi& E, int tid_in) {
;     ...
;             PG8_LDB(B0, 0, 0); PG8_LDB(B1, 0, 1); PG8_SCHED; PG8_LDA(At, 0, 0); PG8_STAGE(PG8_SA(1, 1), a1 + hstep, voffA);
;             PG8_WAIT_V(8); PG8_WAIT_L(0); PG8_BAR; PG8_MMA(0, 0, At, B0); PG8_MMA(0, 1, At, B1); PG8_BAR; PG8_SCHED;
;             PG8_LDA(At, 0, 1); PG8_STAGE(PG8_SB(0, 0), b2, voffB); PG8_STAGE(PG8_SB(0, 1), b2 + hstep, voffB); PG8_STAGE(PG8_SA(0, 0), a2, voffA);
;             PG8_WAIT_V(8); PG8_WAIT_L(0); PG8_BAR; PG8_MMA(1, 0, At, B0); PG8_MMA(1, 1, At, B1); PG8_BAR; PG8_SCHED;
;             PG8_LDB(B0, 1, 0); PG8_LDB(B1, 1, 1); PG8_SCHED; PG8_LDA(At, 1, 0); PG8_STAGE(PG8_SA(0, 1), a2 + hstep, voffA);
;             PG8_WAIT_V(8); PG8_WAIT_L(0); PG8_BAR; PG8_MMA(0, 0, At, B0); PG8_MMA(0, 1, At, B1); PG8_BAR; PG8_SCHED;
;             PG8_LDA(At, 1, 1); PG8_STAGE(PG8_SB(1, 0), b3, voffB); PG8_STAGE(PG8_SB(1, 1), b3 + hstep, voffB); PG8_STAGE(PG8_SA(1, 0), a3, voffA);
;             PG8_WAIT_V(8); PG8_WAIT_L(0); PG8_BAR; PG8_MMA(1, 0, At, B0); PG8_MMA(1, 1, At, B1); PG8_BAR; PG8_SCHED;
	s_add_i32 s24, s58, s35
	v_lshl_add_u64 v[168:169], v[168:169], 0, s[74:75]
	s_mov_b32 m0, s24
	ds_read_b128 v[190:193], v143 offset:49152
	ds_read_b128 v[194:197], v143 offset:50176
	ds_read_b128 v[212:215], v143 offset:51200
	ds_read_b128 v[220:223], v143 offset:52224
	ds_read_b128 v[224:227], v143 offset:53248
	ds_read_b128 v[228:231], v143 offset:54272
	ds_read_b128 v[232:235], v143 offset:55296
	ds_read_b128 v[236:239], v143 offset:56320
	global_load_lds_dwordx4 v[168:169], off
	s_add_i32 m0, s24, 0x2000
	s_add_u32 s24, s28, 0x160080
	v_lshl_add_u64 v[168:169], v[216:217], 0, s[74:75]
	s_addc_u32 s25, s29, 0
	s_add_i32 s28, s59, s35
	global_load_lds_dwordx4 v[168:169], off
	v_lshl_add_u64 v[168:169], s[24:25], 0, v[32:33]
	s_mov_b32 m0, s28
	s_nop 0
	global_load_lds_dwordx4 v[168:169], off
	v_lshl_add_u64 v[168:169], s[24:25], 0, v[130:131]
	s_add_i32 m0, s28, 0x2000
	s_nop 0
	global_load_lds_dwordx4 v[168:169], off
	v_lshl_add_u64 v[168:169], v[240:241], 0, s[74:75]
	s_mov_b32 m0, s48
	s_nop 0
	global_load_lds_dwordx4 v[168:169], off
	v_lshl_add_u64 v[168:169], v[242:243], 0, s[74:75]
	s_mov_b32 m0, s49
	s_nop 0
	global_load_lds_dwordx4 v[168:169], off
	s_waitcnt vmcnt(8)
	s_waitcnt lgkmcnt(0)
	s_setprio 1
	s_barrier
	v_mfma_f32_16x16x32_bf16 v[62:65], v[136:139], v[190:193], v[62:65]
	v_mfma_f32_16x16x32_bf16 v[58:61], v[148:151], v[190:193], v[58:61]
	v_mfma_f32_16x16x32_bf16 v[50:53], v[136:139], v[212:215], v[50:53]
	v_mfma_f32_16x16x32_bf16 v[46:49], v[148:151], v[212:215], v[46:49]
	v_mfma_f32_16x16x32_bf16 v[34:37], v[136:139], v[224:227], v[34:37]
	v_mfma_f32_16x16x32_bf16 v[28:31], v[148:151], v[224:227], v[28:31]
	v_mfma_f32_16x16x32_bf16 v[16:19], v[136:139], v[232:235], v[16:19]
	v_mfma_f32_16x16x32_bf16 v[12:15], v[148:151], v[232:235], v[12:15]
	v_mfma_f32_16x16x32_bf16 v[62:65], v[144:147], v[194:197], v[62:65]
	v_mfma_f32_16x16x32_bf16 v[58:61], v[152:155], v[194:197], v[58:61]
	v_mfma_f32_16x16x32_bf16 v[50:53], v[144:147], v[220:223], v[50:53]
	v_mfma_f32_16x16x32_bf16 v[46:49], v[152:155], v[220:223], v[46:49]
	v_mfma_f32_16x16x32_bf16 v[34:37], v[144:147], v[228:231], v[34:37]
	v_mfma_f32_16x16x32_bf16 v[28:31], v[152:155], v[228:231], v[28:31]
	v_mfma_f32_16x16x32_bf16 v[16:19], v[144:147], v[236:239], v[16:19]
	v_mfma_f32_16x16x32_bf16 v[12:15], v[152:155], v[236:239], v[12:15]
	s_setprio 0
	s_setprio 1
	v_mfma_f32_16x16x32_bf16 v[54:57], v[156:159], v[190:193], v[54:57]
	v_mfma_f32_16x16x32_bf16 v[42:45], v[164:167], v[190:193], v[42:45]
	v_mfma_f32_16x16x32_bf16 v[38:41], v[156:159], v[212:215], v[38:41]
	v_mfma_f32_16x16x32_bf16 v[24:27], v[164:167], v[212:215], v[24:27]
	v_mfma_f32_16x16x32_bf16 v[20:23], v[156:159], v[224:227], v[20:23]
	v_mfma_f32_16x16x32_bf16 v[8:11], v[164:167], v[224:227], v[8:11]
	v_mfma_f32_16x16x32_bf16 v[4:7], v[156:159], v[232:235], v[4:7]
	v_mfma_f32_16x16x32_bf16 v[0:3], v[164:167], v[232:235], v[0:3]
	v_mfma_f32_16x16x32_bf16 v[54:57], v[160:163], v[194:197], v[54:57]
	v_mfma_f32_16x16x32_bf16 v[42:45], v[186:189], v[194:197], v[42:45]
	v_mfma_f32_16x16x32_bf16 v[38:41], v[160:163], v[220:223], v[38:41]
	v_mfma_f32_16x16x32_bf16 v[24:27], v[186:189], v[220:223], v[24:27]
	v_mfma_f32_16x16x32_bf16 v[20:23], v[160:163], v[228:231], v[20:23]
	v_mfma_f32_16x16x32_bf16 v[8:11], v[186:189], v[228:231], v[8:11]
	v_mfma_f32_16x16x32_bf16 v[4:7], v[160:163], v[236:239], v[4:7]
	v_mfma_f32_16x16x32_bf16 v[0:3], v[186:189], v[236:239], v[0:3]
	s_setprio 0
	s_barrier
	s_add_i32 s57, s57, 2
	s_add_u32 s45, s45, 0x100
	s_addc_u32 s47, s47, 0
	s_cmpk_gt_u32 s57, 0x55
	s_mov_b64 s[24:25], s[26:27]
	s_cbranch_scc0 .LBB0_625
	s_and_b64 vcc, exec, s[20:21]
	s_cbranch_vccz .LBB0_628
	s_barrier
